# MFMA order: both K-steps of one accumulator issued back to back (4 of 5 K-loops)
# baseline (speedup 1.0000x reference)
; #define PG8_STAGE(bufoff, gbase, voff) do { _Pragma("unroll") for (int _i = 0; _i < 2; ++_i) { \
;         const unsigned _m0 = ldsb + (unsigned)((bufoff) + _i * 8192); const char* _gb = (const char*)(gbase); \
;         asm volatile("s_mov_b32 m0, %0\n\ts_nop 0\n\tglobal_load_lds_dwordx4 %1, %2" :: "s"(_m0), "v"((voff)[_i]), "s"(_gb) : "m0", "memory"); } } while (0)
; #define PG8_LDA(dst, b, h) do { _Pragma("unroll") for (int m = 0; m < 4; ++m) _Pragma("unroll") for (int k = 0; k < 2; ++k) dst[m][k] = *(const LAS bf16x8*)(lds + PG8_SA(b, h) + aoff + m * 2048 + k * 1024); } while (0)
; #define PG8_LDB(dst, b, h) do { _Pragma("unroll") for (int n = 0; n < 2; ++n) _Pragma("unroll") for (int k = 0; k < 2; ++k) dst[n][k] = *(const LAS bf16x8*)(lds + PG8_SB(b, h) + boff + n * 2048 + k * 1024); } while (0)
; #define PG8_MMA(ai, bj, At, Bt) do { __builtin_amdgcn_s_setprio(1); _Pragma("unroll") for (int m = 0; m < 4; ++m) _Pragma("unroll") for (int n = 0; n < 2; ++n) _Pragma("unroll") for (int k = 0; k < 2; ++k) \
;         acc[ai][bj][m][n] = __builtin_amdgcn_mfma_f32_16x16x32_bf16(Bt[n][k], At[m][k], acc[ai][bj][m][n], 0, 0, 0); __builtin_amdgcn_s_setprio(0); } while (0)
; template <class Epi, bool ALIGN_EPI>
; __device__ __forceinline__ void gemm_phase(LAS unsigned char* lds, const Gemm g, const StaticOrder& S, const Epi& E) {
;     ...
;             PG8_LDB(B0, 0, 0); PG8_LDB(B1, 0, 1); PG8_SCHED; PG8_LDA(At, 0, 0); PG8_STAGE(PG8_SA(1, 1), a1 + hstepA, voffA);
;             PG8_WAIT_V(8); PG8_WAIT_L(0); PG8_BAR; PG8_MMA(0, 0, At, B0); PG8_MMA(0, 1, At, B1); PG8_BAR; PG8_SCHED;
;             PG8_LDA(At, 0, 1); PG8_STAGE(PG8_SB(0, 0), b2, voffB); PG8_STAGE(PG8_SB(0, 1), b2 + hstepB, voffB); PG8_STAGE(PG8_SA(0, 0), a2, voffA);
;             PG8_WAIT_V(8); PG8_WAIT_L(0); PG8_BAR; PG8_MMA(1, 0, At, B0); PG8_MMA(1, 1, At, B1); PG8_BAR; PG8_SCHED;
;             PG8_LDB(B0, 1, 0); PG8_LDB(B1, 1, 1); PG8_SCHED; PG8_LDA(At, 1, 0); PG8_STAGE(PG8_SA(0, 1), a2 + hstepA, voffA);
;             PG8_WAIT_V(8); PG8_WAIT_L(0); PG8_BAR; PG8_MMA(0, 0, At, B0); PG8_MMA(0, 1, At, B1); PG8_BAR; PG8_SCHED;
;             PG8_LDA(At, 1, 1); PG8_STAGE(PG8_SB(1, 0), b3, voffB); PG8_STAGE(PG8_SB(1, 1), b3 + hstepB, voffB); PG8_STAGE(PG8_SA(1, 0), a3, voffA);
;             PG8_WAIT_V(8); PG8_WAIT_L(0); PG8_BAR; PG8_MMA(1, 0, At, B0); PG8_MMA(1, 1, At, B1); PG8_BAR; PG8_SCHED;
.LBB0_151:
	v_add_u32_e32 v132, 0x10000, v244
	v_add_u32_e32 v152, 0x14000, v244
	ds_read_b128 v[108:111], v132
	ds_read_b128 v[120:123], v132 offset:1024
	ds_read_b128 v[128:131], v132 offset:2048
	ds_read_b128 v[132:135], v132 offset:3072
	ds_read_b128 v[136:139], v152
	ds_read_b128 v[144:147], v152 offset:1024
	ds_read_b128 v[148:151], v152 offset:2048
	ds_read_b128 v[152:155], v152 offset:3072
	s_add_i32 s51, s45, 2
	s_cmp_eq_u32 s67, s45
	s_cselect_b32 s56, s0, s37
	s_cselect_b32 s57, s1, s44
	s_cselect_b32 s54, s94, s4
	s_cselect_b32 s55, s95, s5
	s_add_u32 s48, s56, 0x80
	s_addc_u32 s49, s57, 0
	ds_read_b128 v[156:159], v245
	ds_read_b128 v[160:163], v245 offset:1024
	ds_read_b128 v[164:167], v245 offset:2048
	ds_read_b128 v[176:179], v245 offset:3072
	ds_read_b128 v[180:183], v245 offset:4096
	ds_read_b128 v[184:187], v245 offset:5120
	ds_read_b128 v[188:191], v245 offset:6144
	ds_read_b128 v[202:205], v245 offset:7168
	s_add_u32 s45, s37, s15
	s_addc_u32 s59, s44, 0
	s_add_u32 s58, s45, 0xffffff80
	s_addc_u32 s59, s59, -1
	s_mov_b32 m0, s68
	s_nop 0
	global_load_lds_dwordx4 v0, s[58:59]
	s_nop 0
	s_mov_b32 m0, s85
	s_nop 0
	global_load_lds_dwordx4 v240, s[58:59]
	s_waitcnt vmcnt(8)
	s_waitcnt lgkmcnt(0)
	s_barrier
	s_setprio 1
	s_waitcnt lgkmcnt(0)
	v_mfma_f32_16x16x32_bf16 v[172:175], v[108:111], v[156:159], v[172:175]
	v_mfma_f32_16x16x32_bf16 v[172:175], v[120:123], v[160:163], v[172:175]
	v_mfma_f32_16x16x32_bf16 v[168:171], v[128:131], v[156:159], v[168:171]
	v_mfma_f32_16x16x32_bf16 v[168:171], v[132:135], v[160:163], v[168:171]
	v_mfma_f32_16x16x32_bf16 v[140:143], v[136:139], v[156:159], v[140:143]
	v_mfma_f32_16x16x32_bf16 v[140:143], v[144:147], v[160:163], v[140:143]
	v_mfma_f32_16x16x32_bf16 v[124:127], v[148:151], v[156:159], v[124:127]
	v_mfma_f32_16x16x32_bf16 v[124:127], v[152:155], v[160:163], v[124:127]
	v_mfma_f32_16x16x32_bf16 v[100:103], v[148:151], v[164:167], v[100:103]
	v_mfma_f32_16x16x32_bf16 v[100:103], v[152:155], v[176:179], v[100:103]
	v_mfma_f32_16x16x32_bf16 v[104:107], v[136:139], v[164:167], v[104:107]
	v_mfma_f32_16x16x32_bf16 v[104:107], v[144:147], v[176:179], v[104:107]
	v_mfma_f32_16x16x32_bf16 v[112:115], v[128:131], v[164:167], v[112:115]
	v_mfma_f32_16x16x32_bf16 v[112:115], v[132:135], v[176:179], v[112:115]
	v_mfma_f32_16x16x32_bf16 v[116:119], v[108:111], v[164:167], v[116:119]
	v_mfma_f32_16x16x32_bf16 v[116:119], v[120:123], v[176:179], v[116:119]
	v_mfma_f32_16x16x32_bf16 v[96:99], v[108:111], v[180:183], v[96:99]
	v_mfma_f32_16x16x32_bf16 v[96:99], v[120:123], v[184:187], v[96:99]
	v_mfma_f32_16x16x32_bf16 v[92:95], v[128:131], v[180:183], v[92:95]
	v_mfma_f32_16x16x32_bf16 v[92:95], v[132:135], v[184:187], v[92:95]
	v_mfma_f32_16x16x32_bf16 v[88:91], v[136:139], v[180:183], v[88:91]
	v_mfma_f32_16x16x32_bf16 v[88:91], v[144:147], v[184:187], v[88:91]
	v_mfma_f32_16x16x32_bf16 v[84:87], v[148:151], v[180:183], v[84:87]
	v_mfma_f32_16x16x32_bf16 v[84:87], v[152:155], v[184:187], v[84:87]
	v_mfma_f32_16x16x32_bf16 v[68:71], v[148:151], v[188:191], v[68:71]
	v_mfma_f32_16x16x32_bf16 v[68:71], v[152:155], v[202:205], v[68:71]
	v_mfma_f32_16x16x32_bf16 v[72:75], v[136:139], v[188:191], v[72:75]
	v_mfma_f32_16x16x32_bf16 v[72:75], v[144:147], v[202:205], v[72:75]
	v_mfma_f32_16x16x32_bf16 v[76:79], v[128:131], v[188:191], v[76:79]
	v_mfma_f32_16x16x32_bf16 v[76:79], v[132:135], v[202:205], v[76:79]
	v_mfma_f32_16x16x32_bf16 v[80:83], v[108:111], v[188:191], v[80:83]
	v_mfma_f32_16x16x32_bf16 v[80:83], v[120:123], v[202:205], v[80:83]
	s_setprio 0
	s_barrier
	ds_read_b128 v[156:159], v245 offset:16384
	ds_read_b128 v[160:163], v245 offset:17408
	ds_read_b128 v[164:167], v245 offset:18432
	ds_read_b128 v[176:179], v245 offset:19456
	ds_read_b128 v[180:183], v245 offset:20480
	ds_read_b128 v[184:187], v245 offset:21504
	ds_read_b128 v[188:191], v245 offset:22528
	ds_read_b128 v[202:205], v245 offset:23552
	s_mov_b32 m0, s27
	s_nop 0
	global_load_lds_dwordx4 v195, s[54:55]
	s_add_u32 s58, s54, s15
	s_mov_b32 m0, s28
	s_nop 0
	global_load_lds_dwordx4 v241, s[54:55]
	s_addc_u32 s59, s55, 0
	s_mov_b32 m0, s29
	s_nop 0
	global_load_lds_dwordx4 v195, s[58:59]
	s_nop 0
	s_mov_b32 m0, s30
	s_nop 0
	global_load_lds_dwordx4 v241, s[58:59]
	s_nop 0
	s_mov_b32 m0, s26
	s_nop 0
	global_load_lds_dwordx4 v0, s[56:57]
	s_nop 0
	s_mov_b32 m0, s31
	s_nop 0
	global_load_lds_dwordx4 v240, s[56:57]
	s_waitcnt vmcnt(8)
	s_waitcnt lgkmcnt(0)
	s_barrier
	s_setprio 1
	s_waitcnt lgkmcnt(0)
	v_mfma_f32_16x16x32_bf16 v[64:67], v[108:111], v[156:159], v[64:67]
	v_mfma_f32_16x16x32_bf16 v[64:67], v[120:123], v[160:163], v[64:67]
	v_mfma_f32_16x16x32_bf16 v[60:63], v[128:131], v[156:159], v[60:63]
	v_mfma_f32_16x16x32_bf16 v[60:63], v[132:135], v[160:163], v[60:63]
	v_mfma_f32_16x16x32_bf16 v[56:59], v[136:139], v[156:159], v[56:59]
	v_mfma_f32_16x16x32_bf16 v[56:59], v[144:147], v[160:163], v[56:59]
	v_mfma_f32_16x16x32_bf16 v[52:55], v[148:151], v[156:159], v[52:55]
	v_mfma_f32_16x16x32_bf16 v[52:55], v[152:155], v[160:163], v[52:55]
	v_mfma_f32_16x16x32_bf16 v[36:39], v[148:151], v[164:167], v[36:39]
	v_mfma_f32_16x16x32_bf16 v[36:39], v[152:155], v[176:179], v[36:39]
	v_mfma_f32_16x16x32_bf16 v[40:43], v[136:139], v[164:167], v[40:43]
	v_mfma_f32_16x16x32_bf16 v[40:43], v[144:147], v[176:179], v[40:43]
	v_mfma_f32_16x16x32_bf16 v[44:47], v[128:131], v[164:167], v[44:47]
	v_mfma_f32_16x16x32_bf16 v[44:47], v[132:135], v[176:179], v[44:47]
	v_mfma_f32_16x16x32_bf16 v[48:51], v[108:111], v[164:167], v[48:51]
	v_mfma_f32_16x16x32_bf16 v[48:51], v[120:123], v[176:179], v[48:51]
	v_mfma_f32_16x16x32_bf16 v[32:35], v[108:111], v[180:183], v[32:35]
	v_mfma_f32_16x16x32_bf16 v[32:35], v[120:123], v[184:187], v[32:35]
	v_mfma_f32_16x16x32_bf16 v[28:31], v[128:131], v[180:183], v[28:31]
	v_mfma_f32_16x16x32_bf16 v[28:31], v[132:135], v[184:187], v[28:31]
	v_mfma_f32_16x16x32_bf16 v[24:27], v[136:139], v[180:183], v[24:27]
	v_mfma_f32_16x16x32_bf16 v[24:27], v[144:147], v[184:187], v[24:27]
	v_mfma_f32_16x16x32_bf16 v[20:23], v[148:151], v[180:183], v[20:23]
	v_mfma_f32_16x16x32_bf16 v[20:23], v[152:155], v[184:187], v[20:23]
	v_mfma_f32_16x16x32_bf16 v[4:7], v[148:151], v[188:191], v[4:7]
	v_mfma_f32_16x16x32_bf16 v[4:7], v[152:155], v[202:205], v[4:7]
	v_mfma_f32_16x16x32_bf16 v[8:11], v[136:139], v[188:191], v[8:11]
	v_mfma_f32_16x16x32_bf16 v[8:11], v[144:147], v[202:205], v[8:11]
	v_mfma_f32_16x16x32_bf16 v[12:15], v[128:131], v[188:191], v[12:15]
	v_mfma_f32_16x16x32_bf16 v[12:15], v[132:135], v[202:205], v[12:15]
	v_mfma_f32_16x16x32_bf16 v[16:19], v[108:111], v[188:191], v[16:19]
	v_mfma_f32_16x16x32_bf16 v[16:19], v[120:123], v[202:205], v[16:19]
	s_setprio 0
	s_barrier
; #define PG8_STAGE(bufoff, gbase, voff) do { _Pragma("unroll") for (int _i = 0; _i < 2; ++_i) { \
;         const unsigned _m0 = ldsb + (unsigned)((bufoff) + _i * 8192); const char* _gb = (const char*)(gbase); \
;         asm volatile("s_mov_b32 m0, %0\n\ts_nop 0\n\tglobal_load_lds_dwordx4 %1, %2" :: "s"(_m0), "v"((voff)[_i]), "s"(_gb) : "m0", "memory"); } } while (0)
; #define PG8_LDA(dst, b, h) do { _Pragma("unroll") for (int m = 0; m < 4; ++m) _Pragma("unroll") for (int k = 0; k < 2; ++k) dst[m][k] = *(const LAS bf16x8*)(lds + PG8_SA(b, h) + aoff + m * 2048 + k * 1024); } while (0)
; #define PG8_LDB(dst, b, h) do { _Pragma("unroll") for (int n = 0; n < 2; ++n) _Pragma("unroll") for (int k = 0; k < 2; ++k) dst[n][k] = *(const LAS bf16x8*)(lds + PG8_SB(b, h) + boff + n * 2048 + k * 1024); } while (0)
; #define PG8_MMA(ai, bj, At, Bt) do { __builtin_amdgcn_s_setprio(1); _Pragma("unroll") for (int m = 0; m < 4; ++m) _Pragma("unroll") for (int n = 0; n < 2; ++n) _Pragma("unroll") for (int k = 0; k < 2; ++k) \
;         acc[ai][bj][m][n] = __builtin_amdgcn_mfma_f32_16x16x32_bf16(Bt[n][k], At[m][k], acc[ai][bj][m][n], 0, 0, 0); __builtin_amdgcn_s_setprio(0); } while (0)
; template <class Epi, bool ALIGN_EPI>
; __device__ __forceinline__ void gemm_phase(LAS unsigned char* lds, const Gemm g, const StaticOrder& S, const Epi& E) {
;     ...
;             PG8_LDB(B0, 0, 0); PG8_LDB(B1, 0, 1); PG8_SCHED; PG8_LDA(At, 0, 0); PG8_STAGE(PG8_SA(1, 1), a1 + hstepA, voffA);
;             PG8_WAIT_V(8); PG8_WAIT_L(0); PG8_BAR; PG8_MMA(0, 0, At, B0); PG8_MMA(0, 1, At, B1); PG8_BAR; PG8_SCHED;
;             PG8_LDA(At, 0, 1); PG8_STAGE(PG8_SB(0, 0), b2, voffB); PG8_STAGE(PG8_SB(0, 1), b2 + hstepB, voffB); PG8_STAGE(PG8_SA(0, 0), a2, voffA);
;             PG8_WAIT_V(8); PG8_WAIT_L(0); PG8_BAR; PG8_MMA(1, 0, At, B0); PG8_MMA(1, 1, At, B1); PG8_BAR; PG8_SCHED;
;             PG8_LDB(B0, 1, 0); PG8_LDB(B1, 1, 1); PG8_SCHED; PG8_LDA(At, 1, 0); PG8_STAGE(PG8_SA(0, 1), a2 + hstepA, voffA);
;             PG8_WAIT_V(8); PG8_WAIT_L(0); PG8_BAR; PG8_MMA(0, 0, At, B0); PG8_MMA(0, 1, At, B1); PG8_BAR; PG8_SCHED;
;             PG8_LDA(At, 1, 1); PG8_STAGE(PG8_SB(1, 0), b3, voffB); PG8_STAGE(PG8_SB(1, 1), b3 + hstepB, voffB); PG8_STAGE(PG8_SA(1, 0), a3, voffA);
;             PG8_WAIT_V(8); PG8_WAIT_L(0); PG8_BAR; PG8_MMA(1, 0, At, B0); PG8_MMA(1, 1, At, B1); PG8_BAR; PG8_SCHED;
	v_add_u32_e32 v132, 0x18000, v244
	v_add_u32_e32 v152, 0x1c000, v244
	ds_read_b128 v[108:111], v132
	ds_read_b128 v[120:123], v132 offset:1024
	ds_read_b128 v[128:131], v132 offset:2048
	ds_read_b128 v[132:135], v132 offset:3072
	ds_read_b128 v[136:139], v152
	ds_read_b128 v[144:147], v152 offset:1024
	ds_read_b128 v[148:151], v152 offset:2048
	ds_read_b128 v[152:155], v152 offset:3072
	ds_read_b128 v[156:159], v245 offset:32768
	ds_read_b128 v[160:163], v245 offset:33792
	ds_read_b128 v[164:167], v245 offset:34816
	ds_read_b128 v[176:179], v245 offset:35840
	ds_read_b128 v[180:183], v245 offset:36864
	ds_read_b128 v[184:187], v245 offset:37888
	ds_read_b128 v[188:191], v245 offset:38912
	ds_read_b128 v[202:205], v245 offset:39936
	s_add_u32 s56, s56, s15
	s_addc_u32 s57, s57, 0
	s_mov_b32 m0, s41
	s_nop 0
	global_load_lds_dwordx4 v0, s[56:57]
	s_nop 0
	s_mov_b32 m0, s42
	s_nop 0
	global_load_lds_dwordx4 v240, s[56:57]
	s_waitcnt vmcnt(8)
	s_waitcnt lgkmcnt(0)
	s_barrier
	s_setprio 1
	s_waitcnt lgkmcnt(0)
	v_mfma_f32_16x16x32_bf16 v[172:175], v[108:111], v[156:159], v[172:175]
	v_mfma_f32_16x16x32_bf16 v[172:175], v[120:123], v[160:163], v[172:175]
	v_mfma_f32_16x16x32_bf16 v[168:171], v[128:131], v[156:159], v[168:171]
	v_mfma_f32_16x16x32_bf16 v[168:171], v[132:135], v[160:163], v[168:171]
	v_mfma_f32_16x16x32_bf16 v[140:143], v[136:139], v[156:159], v[140:143]
	v_mfma_f32_16x16x32_bf16 v[140:143], v[144:147], v[160:163], v[140:143]
	v_mfma_f32_16x16x32_bf16 v[124:127], v[148:151], v[156:159], v[124:127]
	v_mfma_f32_16x16x32_bf16 v[124:127], v[152:155], v[160:163], v[124:127]
	v_mfma_f32_16x16x32_bf16 v[100:103], v[148:151], v[164:167], v[100:103]
	v_mfma_f32_16x16x32_bf16 v[100:103], v[152:155], v[176:179], v[100:103]
	v_mfma_f32_16x16x32_bf16 v[104:107], v[136:139], v[164:167], v[104:107]
	v_mfma_f32_16x16x32_bf16 v[104:107], v[144:147], v[176:179], v[104:107]
	v_mfma_f32_16x16x32_bf16 v[112:115], v[128:131], v[164:167], v[112:115]
	v_mfma_f32_16x16x32_bf16 v[112:115], v[132:135], v[176:179], v[112:115]
	v_mfma_f32_16x16x32_bf16 v[116:119], v[108:111], v[164:167], v[116:119]
	v_mfma_f32_16x16x32_bf16 v[116:119], v[120:123], v[176:179], v[116:119]
	v_mfma_f32_16x16x32_bf16 v[96:99], v[108:111], v[180:183], v[96:99]
	v_mfma_f32_16x16x32_bf16 v[96:99], v[120:123], v[184:187], v[96:99]
	v_mfma_f32_16x16x32_bf16 v[92:95], v[128:131], v[180:183], v[92:95]
	v_mfma_f32_16x16x32_bf16 v[92:95], v[132:135], v[184:187], v[92:95]
	v_mfma_f32_16x16x32_bf16 v[88:91], v[136:139], v[180:183], v[88:91]
	v_mfma_f32_16x16x32_bf16 v[88:91], v[144:147], v[184:187], v[88:91]
	v_mfma_f32_16x16x32_bf16 v[84:87], v[148:151], v[180:183], v[84:87]
	v_mfma_f32_16x16x32_bf16 v[84:87], v[152:155], v[184:187], v[84:87]
	v_mfma_f32_16x16x32_bf16 v[68:71], v[148:151], v[188:191], v[68:71]
	v_mfma_f32_16x16x32_bf16 v[68:71], v[152:155], v[202:205], v[68:71]
	v_mfma_f32_16x16x32_bf16 v[72:75], v[136:139], v[188:191], v[72:75]
	v_mfma_f32_16x16x32_bf16 v[72:75], v[144:147], v[202:205], v[72:75]
	v_mfma_f32_16x16x32_bf16 v[76:79], v[128:131], v[188:191], v[76:79]
	v_mfma_f32_16x16x32_bf16 v[76:79], v[132:135], v[202:205], v[76:79]
	v_mfma_f32_16x16x32_bf16 v[80:83], v[108:111], v[188:191], v[80:83]
	v_mfma_f32_16x16x32_bf16 v[80:83], v[120:123], v[202:205], v[80:83]
	s_setprio 0
	s_barrier
	ds_read_b128 v[156:159], v245 offset:49152
	ds_read_b128 v[160:163], v245 offset:50176
	ds_read_b128 v[164:167], v245 offset:51200
	ds_read_b128 v[176:179], v245 offset:52224
	ds_read_b128 v[180:183], v245 offset:53248
	ds_read_b128 v[184:187], v245 offset:54272
	ds_read_b128 v[188:191], v245 offset:55296
	ds_read_b128 v[202:205], v245 offset:56320
	s_add_u32 s54, s54, 0x80
	s_addc_u32 s55, s55, 0
	s_mov_b32 m0, s46
	s_nop 0
	global_load_lds_dwordx4 v195, s[54:55]
	s_nop 0
	s_mov_b32 m0, s50
	s_nop 0
	global_load_lds_dwordx4 v241, s[54:55]
	s_add_u32 s54, s58, 0x80
	s_addc_u32 s55, s59, 0
	s_mov_b32 m0, s61
	s_nop 0
	global_load_lds_dwordx4 v195, s[54:55]
	s_nop 0
	s_mov_b32 m0, s65
	s_nop 0
	global_load_lds_dwordx4 v241, s[54:55]
	s_nop 0
	s_mov_b32 m0, s53
	s_nop 0
	global_load_lds_dwordx4 v0, s[48:49]
	s_nop 0
	s_mov_b32 m0, s60
	s_nop 0
	global_load_lds_dwordx4 v240, s[48:49]
	s_waitcnt vmcnt(8)
	s_waitcnt lgkmcnt(0)
	s_barrier
	s_setprio 1
	s_waitcnt lgkmcnt(0)
	v_mfma_f32_16x16x32_bf16 v[64:67], v[108:111], v[156:159], v[64:67]
	v_mfma_f32_16x16x32_bf16 v[64:67], v[120:123], v[160:163], v[64:67]
	v_mfma_f32_16x16x32_bf16 v[60:63], v[128:131], v[156:159], v[60:63]
	v_mfma_f32_16x16x32_bf16 v[60:63], v[132:135], v[160:163], v[60:63]
	v_mfma_f32_16x16x32_bf16 v[56:59], v[136:139], v[156:159], v[56:59]
	v_mfma_f32_16x16x32_bf16 v[56:59], v[144:147], v[160:163], v[56:59]
	v_mfma_f32_16x16x32_bf16 v[52:55], v[148:151], v[156:159], v[52:55]
	v_mfma_f32_16x16x32_bf16 v[52:55], v[152:155], v[160:163], v[52:55]
	v_mfma_f32_16x16x32_bf16 v[36:39], v[148:151], v[164:167], v[36:39]
	v_mfma_f32_16x16x32_bf16 v[36:39], v[152:155], v[176:179], v[36:39]
	v_mfma_f32_16x16x32_bf16 v[40:43], v[136:139], v[164:167], v[40:43]
	v_mfma_f32_16x16x32_bf16 v[40:43], v[144:147], v[176:179], v[40:43]
	v_mfma_f32_16x16x32_bf16 v[44:47], v[128:131], v[164:167], v[44:47]
	v_mfma_f32_16x16x32_bf16 v[44:47], v[132:135], v[176:179], v[44:47]
	v_mfma_f32_16x16x32_bf16 v[48:51], v[108:111], v[164:167], v[48:51]
	v_mfma_f32_16x16x32_bf16 v[48:51], v[120:123], v[176:179], v[48:51]
	v_mfma_f32_16x16x32_bf16 v[32:35], v[108:111], v[180:183], v[32:35]
	v_mfma_f32_16x16x32_bf16 v[32:35], v[120:123], v[184:187], v[32:35]
	v_mfma_f32_16x16x32_bf16 v[28:31], v[128:131], v[180:183], v[28:31]
	v_mfma_f32_16x16x32_bf16 v[28:31], v[132:135], v[184:187], v[28:31]
	v_mfma_f32_16x16x32_bf16 v[24:27], v[136:139], v[180:183], v[24:27]
	v_mfma_f32_16x16x32_bf16 v[24:27], v[144:147], v[184:187], v[24:27]
	v_mfma_f32_16x16x32_bf16 v[20:23], v[148:151], v[180:183], v[20:23]
	v_mfma_f32_16x16x32_bf16 v[20:23], v[152:155], v[184:187], v[20:23]
	v_mfma_f32_16x16x32_bf16 v[4:7], v[148:151], v[188:191], v[4:7]
	v_mfma_f32_16x16x32_bf16 v[4:7], v[152:155], v[202:205], v[4:7]
	v_mfma_f32_16x16x32_bf16 v[8:11], v[136:139], v[188:191], v[8:11]
	v_mfma_f32_16x16x32_bf16 v[8:11], v[144:147], v[202:205], v[8:11]
	v_mfma_f32_16x16x32_bf16 v[12:15], v[128:131], v[188:191], v[12:15]
	v_mfma_f32_16x16x32_bf16 v[12:15], v[132:135], v[202:205], v[12:15]
	v_mfma_f32_16x16x32_bf16 v[16:19], v[108:111], v[188:191], v[16:19]
	v_mfma_f32_16x16x32_bf16 v[16:19], v[120:123], v[202:205], v[16:19]
	s_setprio 0
	s_barrier
	s_add_u32 s4, s4, 0x100
	s_addc_u32 s5, s5, 0
	s_add_u32 s37, s37, 0x100
	s_addc_u32 s44, s44, 0
	s_cmp_ge_u32 s51, s43
	s_mov_b32 s45, s51
	s_cbranch_scc0 .LBB0_151
	s_and_b64 vcc, exec, s[92:93]
	s_cbranch_vccz .LBB0_154
	s_barrier

; #define PG8_STAGE(bufoff, gbase, voff) do { _Pragma("unroll") for (int _i = 0; _i < 2; ++_i) { \
;         const unsigned _m0 = ldsb + (unsigned)((bufoff) + _i * 8192); const char* _gb = (const char*)(gbase); \
;         asm volatile("s_mov_b32 m0, %0\n\ts_nop 0\n\tglobal_load_lds_dwordx4 %1, %2" :: "s"(_m0), "v"((voff)[_i]), "s"(_gb) : "m0", "memory"); } } while (0)
; #define PG8_LDA(dst, b, h) do { _Pragma("unroll") for (int m = 0; m < 4; ++m) _Pragma("unroll") for (int k = 0; k < 2; ++k) dst[m][k] = *(const LAS bf16x8*)(lds + PG8_SA(b, h) + aoff + m * 2048 + k * 1024); } while (0)
; #define PG8_LDB(dst, b, h) do { _Pragma("unroll") for (int n = 0; n < 2; ++n) _Pragma("unroll") for (int k = 0; k < 2; ++k) dst[n][k] = *(const LAS bf16x8*)(lds + PG8_SB(b, h) + boff + n * 2048 + k * 1024); } while (0)
; #define PG8_MMA(ai, bj, At, Bt) do { __builtin_amdgcn_s_setprio(1); _Pragma("unroll") for (int m = 0; m < 4; ++m) _Pragma("unroll") for (int n = 0; n < 2; ++n) _Pragma("unroll") for (int k = 0; k < 2; ++k) \
;         acc[ai][bj][m][n] = __builtin_amdgcn_mfma_f32_16x16x32_bf16(Bt[n][k], At[m][k], acc[ai][bj][m][n], 0, 0, 0); __builtin_amdgcn_s_setprio(0); } while (0)
; template <class Epi, bool ALIGN_EPI>
; __device__ __forceinline__ void gemm_phase(LAS unsigned char* lds, const Gemm g, const StaticOrder& S, const Epi& E) {
;     ...
;             PG8_LDB(B0, 0, 0); PG8_LDB(B1, 0, 1); PG8_SCHED; PG8_LDA(At, 0, 0); PG8_STAGE(PG8_SA(1, 1), a1 + hstepA, voffA);
;             PG8_WAIT_V(8); PG8_WAIT_L(0); PG8_BAR; PG8_MMA(0, 0, At, B0); PG8_MMA(0, 1, At, B1); PG8_BAR; PG8_SCHED;
;             PG8_LDA(At, 0, 1); PG8_STAGE(PG8_SB(0, 0), b2, voffB); PG8_STAGE(PG8_SB(0, 1), b2 + hstepB, voffB); PG8_STAGE(PG8_SA(0, 0), a2, voffA);
;             PG8_WAIT_V(8); PG8_WAIT_L(0); PG8_BAR; PG8_MMA(1, 0, At, B0); PG8_MMA(1, 1, At, B1); PG8_BAR; PG8_SCHED;
;             PG8_LDB(B0, 1, 0); PG8_LDB(B1, 1, 1); PG8_SCHED; PG8_LDA(At, 1, 0); PG8_STAGE(PG8_SA(0, 1), a2 + hstepA, voffA);
;             PG8_WAIT_V(8); PG8_WAIT_L(0); PG8_BAR; PG8_MMA(0, 0, At, B0); PG8_MMA(0, 1, At, B1); PG8_BAR; PG8_SCHED;
;             PG8_LDA(At, 1, 1); PG8_STAGE(PG8_SB(1, 0), b3, voffB); PG8_STAGE(PG8_SB(1, 1), b3 + hstepB, voffB); PG8_STAGE(PG8_SA(1, 0), a3, voffA);
;             PG8_WAIT_V(8); PG8_WAIT_L(0); PG8_BAR; PG8_MMA(1, 0, At, B0); PG8_MMA(1, 1, At, B1); PG8_BAR; PG8_SCHED;
.LBB0_201:
	v_add_u32_e32 v142, 0x10000, v245
	v_add_u32_e32 v158, 0x14000, v245
	ds_read_b128 v[130:133], v142
	ds_read_b128 v[134:137], v142 offset:1024
	ds_read_b128 v[138:141], v142 offset:2048
	ds_read_b128 v[142:145], v142 offset:3072
	ds_read_b128 v[146:149], v158
	ds_read_b128 v[150:153], v158 offset:1024
	ds_read_b128 v[154:157], v158 offset:2048
	ds_read_b128 v[158:161], v158 offset:3072
	s_add_i32 s44, s43, 2
	s_cmp_eq_u32 s68, s43
	s_cselect_b32 s56, s0, s15
	s_cselect_b32 s57, s1, s42
	s_cselect_b32 s54, s94, s4
	s_cselect_b32 s55, s95, s5
	s_add_u32 s48, s56, 0x80
	s_addc_u32 s49, s57, 0
	ds_read_b128 v[162:165], v246
	ds_read_b128 v[166:169], v246 offset:1024
	ds_read_b128 v[170:173], v246 offset:2048
	ds_read_b128 v[174:177], v246 offset:3072
	ds_read_b128 v[178:181], v246 offset:4096
	ds_read_b128 v[182:185], v246 offset:5120
	ds_read_b128 v[186:189], v246 offset:6144
	ds_read_b128 v[190:193], v246 offset:7168
	s_add_u32 s43, s15, s38
	s_addc_u32 s45, s42, 0
	s_add_u32 s58, s43, 0xffffff80
	s_addc_u32 s59, s45, -1
	s_mov_b32 m0, s37
	s_nop 0
	global_load_lds_dwordx4 v0, s[58:59]
	s_nop 0
	s_mov_b32 m0, s41
	s_nop 0
	global_load_lds_dwordx4 v206, s[58:59]
	s_waitcnt vmcnt(8)
	s_waitcnt lgkmcnt(0)
	s_barrier
	s_setprio 1
	s_waitcnt lgkmcnt(0)
	v_mfma_f32_16x16x32_bf16 v[126:129], v[130:133], v[162:165], v[126:129]
	v_mfma_f32_16x16x32_bf16 v[126:129], v[134:137], v[166:169], v[126:129]
	v_mfma_f32_16x16x32_bf16 v[122:125], v[138:141], v[162:165], v[122:125]
	v_mfma_f32_16x16x32_bf16 v[122:125], v[142:145], v[166:169], v[122:125]
	v_mfma_f32_16x16x32_bf16 v[118:121], v[146:149], v[162:165], v[118:121]
	v_mfma_f32_16x16x32_bf16 v[118:121], v[150:153], v[166:169], v[118:121]
	v_mfma_f32_16x16x32_bf16 v[114:117], v[154:157], v[162:165], v[114:117]
	v_mfma_f32_16x16x32_bf16 v[114:117], v[158:161], v[166:169], v[114:117]
	v_mfma_f32_16x16x32_bf16 v[98:101], v[154:157], v[170:173], v[98:101]
	v_mfma_f32_16x16x32_bf16 v[98:101], v[158:161], v[174:177], v[98:101]
	v_mfma_f32_16x16x32_bf16 v[102:105], v[146:149], v[170:173], v[102:105]
	v_mfma_f32_16x16x32_bf16 v[102:105], v[150:153], v[174:177], v[102:105]
	v_mfma_f32_16x16x32_bf16 v[106:109], v[138:141], v[170:173], v[106:109]
	v_mfma_f32_16x16x32_bf16 v[106:109], v[142:145], v[174:177], v[106:109]
	v_mfma_f32_16x16x32_bf16 v[110:113], v[130:133], v[170:173], v[110:113]
	v_mfma_f32_16x16x32_bf16 v[110:113], v[134:137], v[174:177], v[110:113]
	v_mfma_f32_16x16x32_bf16 v[94:97], v[130:133], v[178:181], v[94:97]
	v_mfma_f32_16x16x32_bf16 v[94:97], v[134:137], v[182:185], v[94:97]
	v_mfma_f32_16x16x32_bf16 v[90:93], v[138:141], v[178:181], v[90:93]
	v_mfma_f32_16x16x32_bf16 v[90:93], v[142:145], v[182:185], v[90:93]
	v_mfma_f32_16x16x32_bf16 v[86:89], v[146:149], v[178:181], v[86:89]
	v_mfma_f32_16x16x32_bf16 v[86:89], v[150:153], v[182:185], v[86:89]
	v_mfma_f32_16x16x32_bf16 v[82:85], v[154:157], v[178:181], v[82:85]
	v_mfma_f32_16x16x32_bf16 v[82:85], v[158:161], v[182:185], v[82:85]
	v_mfma_f32_16x16x32_bf16 v[66:69], v[154:157], v[186:189], v[66:69]
	v_mfma_f32_16x16x32_bf16 v[66:69], v[158:161], v[190:193], v[66:69]
	v_mfma_f32_16x16x32_bf16 v[70:73], v[146:149], v[186:189], v[70:73]
	v_mfma_f32_16x16x32_bf16 v[70:73], v[150:153], v[190:193], v[70:73]
	v_mfma_f32_16x16x32_bf16 v[74:77], v[138:141], v[186:189], v[74:77]
	v_mfma_f32_16x16x32_bf16 v[74:77], v[142:145], v[190:193], v[74:77]
	v_mfma_f32_16x16x32_bf16 v[78:81], v[130:133], v[186:189], v[78:81]
	v_mfma_f32_16x16x32_bf16 v[78:81], v[134:137], v[190:193], v[78:81]
	s_setprio 0
	s_barrier
	ds_read_b128 v[162:165], v246 offset:16384
	ds_read_b128 v[166:169], v246 offset:17408
	ds_read_b128 v[170:173], v246 offset:18432
	ds_read_b128 v[174:177], v246 offset:19456
	ds_read_b128 v[178:181], v246 offset:20480
	ds_read_b128 v[182:185], v246 offset:21504
	ds_read_b128 v[186:189], v246 offset:22528
	ds_read_b128 v[190:193], v246 offset:23552
	s_mov_b32 m0, s46
	s_nop 0
	global_load_lds_dwordx4 v195, s[54:55]
	s_add_u32 s58, s54, s38
	s_mov_b32 m0, s26
	s_nop 0
	global_load_lds_dwordx4 v207, s[54:55]
	s_addc_u32 s59, s55, 0
	s_mov_b32 m0, s27
	s_nop 0
	global_load_lds_dwordx4 v195, s[58:59]
	s_nop 0
	s_mov_b32 m0, s30
	s_nop 0
	global_load_lds_dwordx4 v207, s[58:59]
	s_nop 0
	s_mov_b32 m0, s29
	s_nop 0
	global_load_lds_dwordx4 v0, s[56:57]
	s_nop 0
	s_mov_b32 m0, s17
	s_nop 0
	global_load_lds_dwordx4 v206, s[56:57]
	s_waitcnt vmcnt(8)
	s_waitcnt lgkmcnt(0)
	s_barrier
	s_setprio 1
	s_waitcnt lgkmcnt(0)
	v_mfma_f32_16x16x32_bf16 v[62:65], v[130:133], v[162:165], v[62:65]
	v_mfma_f32_16x16x32_bf16 v[62:65], v[134:137], v[166:169], v[62:65]
	v_mfma_f32_16x16x32_bf16 v[58:61], v[138:141], v[162:165], v[58:61]
	v_mfma_f32_16x16x32_bf16 v[58:61], v[142:145], v[166:169], v[58:61]
	v_mfma_f32_16x16x32_bf16 v[54:57], v[146:149], v[162:165], v[54:57]
	v_mfma_f32_16x16x32_bf16 v[54:57], v[150:153], v[166:169], v[54:57]
	v_mfma_f32_16x16x32_bf16 v[50:53], v[154:157], v[162:165], v[50:53]
	v_mfma_f32_16x16x32_bf16 v[50:53], v[158:161], v[166:169], v[50:53]
	v_mfma_f32_16x16x32_bf16 v[34:37], v[154:157], v[170:173], v[34:37]
	v_mfma_f32_16x16x32_bf16 v[34:37], v[158:161], v[174:177], v[34:37]
	v_mfma_f32_16x16x32_bf16 v[38:41], v[146:149], v[170:173], v[38:41]
	v_mfma_f32_16x16x32_bf16 v[38:41], v[150:153], v[174:177], v[38:41]
	v_mfma_f32_16x16x32_bf16 v[42:45], v[138:141], v[170:173], v[42:45]
	v_mfma_f32_16x16x32_bf16 v[42:45], v[142:145], v[174:177], v[42:45]
	v_mfma_f32_16x16x32_bf16 v[46:49], v[130:133], v[170:173], v[46:49]
	v_mfma_f32_16x16x32_bf16 v[46:49], v[134:137], v[174:177], v[46:49]
	v_mfma_f32_16x16x32_bf16 v[30:33], v[130:133], v[178:181], v[30:33]
	v_mfma_f32_16x16x32_bf16 v[30:33], v[134:137], v[182:185], v[30:33]
	v_mfma_f32_16x16x32_bf16 v[26:29], v[138:141], v[178:181], v[26:29]
	v_mfma_f32_16x16x32_bf16 v[26:29], v[142:145], v[182:185], v[26:29]
	v_mfma_f32_16x16x32_bf16 v[22:25], v[146:149], v[178:181], v[22:25]
	v_mfma_f32_16x16x32_bf16 v[22:25], v[150:153], v[182:185], v[22:25]
	v_mfma_f32_16x16x32_bf16 v[18:21], v[154:157], v[178:181], v[18:21]
	v_mfma_f32_16x16x32_bf16 v[18:21], v[158:161], v[182:185], v[18:21]
	v_mfma_f32_16x16x32_bf16 v[2:5], v[154:157], v[186:189], v[2:5]
	v_mfma_f32_16x16x32_bf16 v[2:5], v[158:161], v[190:193], v[2:5]
	v_mfma_f32_16x16x32_bf16 v[6:9], v[146:149], v[186:189], v[6:9]
	v_mfma_f32_16x16x32_bf16 v[6:9], v[150:153], v[190:193], v[6:9]
	v_mfma_f32_16x16x32_bf16 v[10:13], v[138:141], v[186:189], v[10:13]
	v_mfma_f32_16x16x32_bf16 v[10:13], v[142:145], v[190:193], v[10:13]
	v_mfma_f32_16x16x32_bf16 v[14:17], v[130:133], v[186:189], v[14:17]
	v_mfma_f32_16x16x32_bf16 v[14:17], v[134:137], v[190:193], v[14:17]
	s_setprio 0
	s_barrier
; #define PG8_STAGE(bufoff, gbase, voff) do { _Pragma("unroll") for (int _i = 0; _i < 2; ++_i) { \
;         const unsigned _m0 = ldsb + (unsigned)((bufoff) + _i * 8192); const char* _gb = (const char*)(gbase); \
;         asm volatile("s_mov_b32 m0, %0\n\ts_nop 0\n\tglobal_load_lds_dwordx4 %1, %2" :: "s"(_m0), "v"((voff)[_i]), "s"(_gb) : "m0", "memory"); } } while (0)
; #define PG8_LDA(dst, b, h) do { _Pragma("unroll") for (int m = 0; m < 4; ++m) _Pragma("unroll") for (int k = 0; k < 2; ++k) dst[m][k] = *(const LAS bf16x8*)(lds + PG8_SA(b, h) + aoff + m * 2048 + k * 1024); } while (0)
; #define PG8_LDB(dst, b, h) do { _Pragma("unroll") for (int n = 0; n < 2; ++n) _Pragma("unroll") for (int k = 0; k < 2; ++k) dst[n][k] = *(const LAS bf16x8*)(lds + PG8_SB(b, h) + boff + n * 2048 + k * 1024); } while (0)
; #define PG8_MMA(ai, bj, At, Bt) do { __builtin_amdgcn_s_setprio(1); _Pragma("unroll") for (int m = 0; m < 4; ++m) _Pragma("unroll") for (int n = 0; n < 2; ++n) _Pragma("unroll") for (int k = 0; k < 2; ++k) \
;         acc[ai][bj][m][n] = __builtin_amdgcn_mfma_f32_16x16x32_bf16(Bt[n][k], At[m][k], acc[ai][bj][m][n], 0, 0, 0); __builtin_amdgcn_s_setprio(0); } while (0)
; template <class Epi, bool ALIGN_EPI>
; __device__ __forceinline__ void gemm_phase(LAS unsigned char* lds, const Gemm g, const StaticOrder& S, const Epi& E) {
;     ...
;             PG8_LDB(B0, 0, 0); PG8_LDB(B1, 0, 1); PG8_SCHED; PG8_LDA(At, 0, 0); PG8_STAGE(PG8_SA(1, 1), a1 + hstepA, voffA);
;             PG8_WAIT_V(8); PG8_WAIT_L(0); PG8_BAR; PG8_MMA(0, 0, At, B0); PG8_MMA(0, 1, At, B1); PG8_BAR; PG8_SCHED;
;             PG8_LDA(At, 0, 1); PG8_STAGE(PG8_SB(0, 0), b2, voffB); PG8_STAGE(PG8_SB(0, 1), b2 + hstepB, voffB); PG8_STAGE(PG8_SA(0, 0), a2, voffA);
;             PG8_WAIT_V(8); PG8_WAIT_L(0); PG8_BAR; PG8_MMA(1, 0, At, B0); PG8_MMA(1, 1, At, B1); PG8_BAR; PG8_SCHED;
;             PG8_LDB(B0, 1, 0); PG8_LDB(B1, 1, 1); PG8_SCHED; PG8_LDA(At, 1, 0); PG8_STAGE(PG8_SA(0, 1), a2 + hstepA, voffA);
;             PG8_WAIT_V(8); PG8_WAIT_L(0); PG8_BAR; PG8_MMA(0, 0, At, B0); PG8_MMA(0, 1, At, B1); PG8_BAR; PG8_SCHED;
;             PG8_LDA(At, 1, 1); PG8_STAGE(PG8_SB(1, 0), b3, voffB); PG8_STAGE(PG8_SB(1, 1), b3 + hstepB, voffB); PG8_STAGE(PG8_SA(1, 0), a3, voffA);
;             PG8_WAIT_V(8); PG8_WAIT_L(0); PG8_BAR; PG8_MMA(1, 0, At, B0); PG8_MMA(1, 1, At, B1); PG8_BAR; PG8_SCHED;
	v_add_u32_e32 v142, 0x18000, v245
	v_add_u32_e32 v158, 0x1c000, v245
	ds_read_b128 v[130:133], v142
	ds_read_b128 v[134:137], v142 offset:1024
	ds_read_b128 v[138:141], v142 offset:2048
	ds_read_b128 v[142:145], v142 offset:3072
	ds_read_b128 v[146:149], v158
	ds_read_b128 v[150:153], v158 offset:1024
	ds_read_b128 v[154:157], v158 offset:2048
	ds_read_b128 v[158:161], v158 offset:3072
	ds_read_b128 v[162:165], v246 offset:32768
	ds_read_b128 v[166:169], v246 offset:33792
	ds_read_b128 v[170:173], v246 offset:34816
	ds_read_b128 v[174:177], v246 offset:35840
	ds_read_b128 v[178:181], v246 offset:36864
	ds_read_b128 v[182:185], v246 offset:37888
	ds_read_b128 v[186:189], v246 offset:38912
	ds_read_b128 v[190:193], v246 offset:39936
	s_add_u32 s56, s56, s38
	s_addc_u32 s57, s57, 0
	s_mov_b32 m0, s31
	s_nop 0
	global_load_lds_dwordx4 v0, s[56:57]
	s_nop 0
	s_mov_b32 m0, s53
	s_nop 0
	global_load_lds_dwordx4 v206, s[56:57]
	s_waitcnt vmcnt(8)
	s_waitcnt lgkmcnt(0)
	s_barrier
	s_setprio 1
	s_waitcnt lgkmcnt(0)
	v_mfma_f32_16x16x32_bf16 v[126:129], v[130:133], v[162:165], v[126:129]
	v_mfma_f32_16x16x32_bf16 v[126:129], v[134:137], v[166:169], v[126:129]
	v_mfma_f32_16x16x32_bf16 v[122:125], v[138:141], v[162:165], v[122:125]
	v_mfma_f32_16x16x32_bf16 v[122:125], v[142:145], v[166:169], v[122:125]
	v_mfma_f32_16x16x32_bf16 v[118:121], v[146:149], v[162:165], v[118:121]
	v_mfma_f32_16x16x32_bf16 v[118:121], v[150:153], v[166:169], v[118:121]
	v_mfma_f32_16x16x32_bf16 v[114:117], v[154:157], v[162:165], v[114:117]
	v_mfma_f32_16x16x32_bf16 v[114:117], v[158:161], v[166:169], v[114:117]
	v_mfma_f32_16x16x32_bf16 v[98:101], v[154:157], v[170:173], v[98:101]
	v_mfma_f32_16x16x32_bf16 v[98:101], v[158:161], v[174:177], v[98:101]
	v_mfma_f32_16x16x32_bf16 v[102:105], v[146:149], v[170:173], v[102:105]
	v_mfma_f32_16x16x32_bf16 v[102:105], v[150:153], v[174:177], v[102:105]
	v_mfma_f32_16x16x32_bf16 v[106:109], v[138:141], v[170:173], v[106:109]
	v_mfma_f32_16x16x32_bf16 v[106:109], v[142:145], v[174:177], v[106:109]
	v_mfma_f32_16x16x32_bf16 v[110:113], v[130:133], v[170:173], v[110:113]
	v_mfma_f32_16x16x32_bf16 v[110:113], v[134:137], v[174:177], v[110:113]
	v_mfma_f32_16x16x32_bf16 v[94:97], v[130:133], v[178:181], v[94:97]
	v_mfma_f32_16x16x32_bf16 v[94:97], v[134:137], v[182:185], v[94:97]
	v_mfma_f32_16x16x32_bf16 v[90:93], v[138:141], v[178:181], v[90:93]
	v_mfma_f32_16x16x32_bf16 v[90:93], v[142:145], v[182:185], v[90:93]
	v_mfma_f32_16x16x32_bf16 v[86:89], v[146:149], v[178:181], v[86:89]
	v_mfma_f32_16x16x32_bf16 v[86:89], v[150:153], v[182:185], v[86:89]
	v_mfma_f32_16x16x32_bf16 v[82:85], v[154:157], v[178:181], v[82:85]
	v_mfma_f32_16x16x32_bf16 v[82:85], v[158:161], v[182:185], v[82:85]
	v_mfma_f32_16x16x32_bf16 v[66:69], v[154:157], v[186:189], v[66:69]
	v_mfma_f32_16x16x32_bf16 v[66:69], v[158:161], v[190:193], v[66:69]
	v_mfma_f32_16x16x32_bf16 v[70:73], v[146:149], v[186:189], v[70:73]
	v_mfma_f32_16x16x32_bf16 v[70:73], v[150:153], v[190:193], v[70:73]
	v_mfma_f32_16x16x32_bf16 v[74:77], v[138:141], v[186:189], v[74:77]
	v_mfma_f32_16x16x32_bf16 v[74:77], v[142:145], v[190:193], v[74:77]
	v_mfma_f32_16x16x32_bf16 v[78:81], v[130:133], v[186:189], v[78:81]
	v_mfma_f32_16x16x32_bf16 v[78:81], v[134:137], v[190:193], v[78:81]
	s_setprio 0
	s_barrier
	ds_read_b128 v[162:165], v246 offset:49152
	ds_read_b128 v[166:169], v246 offset:50176
	ds_read_b128 v[170:173], v246 offset:51200
	ds_read_b128 v[174:177], v246 offset:52224
	ds_read_b128 v[178:181], v246 offset:53248
	ds_read_b128 v[182:185], v246 offset:54272
	ds_read_b128 v[186:189], v246 offset:55296
	ds_read_b128 v[190:193], v246 offset:56320
	s_add_u32 s54, s54, 0x80
	s_addc_u32 s55, s55, 0
	s_mov_b32 m0, s85
	s_nop 0
	global_load_lds_dwordx4 v195, s[54:55]
	s_nop 0
	s_mov_b32 m0, s65
	s_nop 0
	global_load_lds_dwordx4 v207, s[54:55]
	s_add_u32 s54, s58, 0x80
	s_addc_u32 s55, s59, 0
	s_mov_b32 m0, s93
	s_nop 0
	global_load_lds_dwordx4 v195, s[54:55]
	s_nop 0
	s_mov_b32 m0, s28
	s_nop 0
	global_load_lds_dwordx4 v207, s[54:55]
	s_nop 0
	s_mov_b32 m0, s67
	s_nop 0
	global_load_lds_dwordx4 v0, s[48:49]
	s_nop 0
	s_mov_b32 m0, s92
	s_nop 0
	global_load_lds_dwordx4 v206, s[48:49]
	s_waitcnt vmcnt(8)
	s_waitcnt lgkmcnt(0)
	s_barrier
	s_setprio 1
	s_waitcnt lgkmcnt(0)
	v_mfma_f32_16x16x32_bf16 v[62:65], v[130:133], v[162:165], v[62:65]
	v_mfma_f32_16x16x32_bf16 v[62:65], v[134:137], v[166:169], v[62:65]
	v_mfma_f32_16x16x32_bf16 v[58:61], v[138:141], v[162:165], v[58:61]
	v_mfma_f32_16x16x32_bf16 v[58:61], v[142:145], v[166:169], v[58:61]
	v_mfma_f32_16x16x32_bf16 v[54:57], v[146:149], v[162:165], v[54:57]
	v_mfma_f32_16x16x32_bf16 v[54:57], v[150:153], v[166:169], v[54:57]
	v_mfma_f32_16x16x32_bf16 v[50:53], v[154:157], v[162:165], v[50:53]
	v_mfma_f32_16x16x32_bf16 v[50:53], v[158:161], v[166:169], v[50:53]
	v_mfma_f32_16x16x32_bf16 v[34:37], v[154:157], v[170:173], v[34:37]
	v_mfma_f32_16x16x32_bf16 v[34:37], v[158:161], v[174:177], v[34:37]
	v_mfma_f32_16x16x32_bf16 v[38:41], v[146:149], v[170:173], v[38:41]
	v_mfma_f32_16x16x32_bf16 v[38:41], v[150:153], v[174:177], v[38:41]
	v_mfma_f32_16x16x32_bf16 v[42:45], v[138:141], v[170:173], v[42:45]
	v_mfma_f32_16x16x32_bf16 v[42:45], v[142:145], v[174:177], v[42:45]
	v_mfma_f32_16x16x32_bf16 v[46:49], v[130:133], v[170:173], v[46:49]
	v_mfma_f32_16x16x32_bf16 v[46:49], v[134:137], v[174:177], v[46:49]
	v_mfma_f32_16x16x32_bf16 v[30:33], v[130:133], v[178:181], v[30:33]
	v_mfma_f32_16x16x32_bf16 v[30:33], v[134:137], v[182:185], v[30:33]
	v_mfma_f32_16x16x32_bf16 v[26:29], v[138:141], v[178:181], v[26:29]
	v_mfma_f32_16x16x32_bf16 v[26:29], v[142:145], v[182:185], v[26:29]
	v_mfma_f32_16x16x32_bf16 v[22:25], v[146:149], v[178:181], v[22:25]
	v_mfma_f32_16x16x32_bf16 v[22:25], v[150:153], v[182:185], v[22:25]
	v_mfma_f32_16x16x32_bf16 v[18:21], v[154:157], v[178:181], v[18:21]
	v_mfma_f32_16x16x32_bf16 v[18:21], v[158:161], v[182:185], v[18:21]
	v_mfma_f32_16x16x32_bf16 v[2:5], v[154:157], v[186:189], v[2:5]
	v_mfma_f32_16x16x32_bf16 v[2:5], v[158:161], v[190:193], v[2:5]
	v_mfma_f32_16x16x32_bf16 v[6:9], v[146:149], v[186:189], v[6:9]
	v_mfma_f32_16x16x32_bf16 v[6:9], v[150:153], v[190:193], v[6:9]
	v_mfma_f32_16x16x32_bf16 v[10:13], v[138:141], v[186:189], v[10:13]
	v_mfma_f32_16x16x32_bf16 v[10:13], v[142:145], v[190:193], v[10:13]
	v_mfma_f32_16x16x32_bf16 v[14:17], v[130:133], v[186:189], v[14:17]
	v_mfma_f32_16x16x32_bf16 v[14:17], v[134:137], v[190:193], v[14:17]
	s_setprio 0
	s_barrier
	s_add_u32 s4, s4, 0x100
	s_addc_u32 s5, s5, 0
	s_add_u32 s15, s15, 0x100
	s_addc_u32 s42, s42, 0
	s_cmp_ge_u32 s44, s36
	s_mov_b32 s43, s44
	s_cbranch_scc0 .LBB0_201
	v_readlane_b32 s4, v255, 6
	v_readlane_b32 s5, v255, 7
	s_and_b64 vcc, exec, s[4:5]
	s_cbranch_vccz .LBB0_204
	s_barrier

; #define PG8_STAGE(bufoff, gbase, voff) do { _Pragma("unroll") for (int _i = 0; _i < 2; ++_i) { \
;         const unsigned _m0 = ldsb + (unsigned)((bufoff) + _i * 8192); const char* _gb = (const char*)(gbase); \
;         asm volatile("s_mov_b32 m0, %0\n\ts_nop 0\n\tglobal_load_lds_dwordx4 %1, %2" :: "s"(_m0), "v"((voff)[_i]), "s"(_gb) : "m0", "memory"); } } while (0)
; #define PG8_LDA(dst, b, h) do { _Pragma("unroll") for (int m = 0; m < 4; ++m) _Pragma("unroll") for (int k = 0; k < 2; ++k) dst[m][k] = *(const LAS bf16x8*)(lds + PG8_SA(b, h) + aoff + m * 2048 + k * 1024); } while (0)
; #define PG8_LDB(dst, b, h) do { _Pragma("unroll") for (int n = 0; n < 2; ++n) _Pragma("unroll") for (int k = 0; k < 2; ++k) dst[n][k] = *(const LAS bf16x8*)(lds + PG8_SB(b, h) + boff + n * 2048 + k * 1024); } while (0)
; #define PG8_MMA(ai, bj, At, Bt) do { __builtin_amdgcn_s_setprio(1); _Pragma("unroll") for (int m = 0; m < 4; ++m) _Pragma("unroll") for (int n = 0; n < 2; ++n) _Pragma("unroll") for (int k = 0; k < 2; ++k) \
;         acc[ai][bj][m][n] = __builtin_amdgcn_mfma_f32_16x16x32_bf16(Bt[n][k], At[m][k], acc[ai][bj][m][n], 0, 0, 0); __builtin_amdgcn_s_setprio(0); } while (0)
; template <class Epi, bool ALIGN_EPI>
; __device__ __forceinline__ void gemm_phase(LAS unsigned char* lds, const Gemm g, const StaticOrder& S, const Epi& E) {
;     ...
;             PG8_LDB(B0, 0, 0); PG8_LDB(B1, 0, 1); PG8_SCHED; PG8_LDA(At, 0, 0); PG8_STAGE(PG8_SA(1, 1), a1 + hstepA, voffA);
;             PG8_WAIT_V(8); PG8_WAIT_L(0); PG8_BAR; PG8_MMA(0, 0, At, B0); PG8_MMA(0, 1, At, B1); PG8_BAR; PG8_SCHED;
;             PG8_LDA(At, 0, 1); PG8_STAGE(PG8_SB(0, 0), b2, voffB); PG8_STAGE(PG8_SB(0, 1), b2 + hstepB, voffB); PG8_STAGE(PG8_SA(0, 0), a2, voffA);
;             PG8_WAIT_V(8); PG8_WAIT_L(0); PG8_BAR; PG8_MMA(1, 0, At, B0); PG8_MMA(1, 1, At, B1); PG8_BAR; PG8_SCHED;
;             PG8_LDB(B0, 1, 0); PG8_LDB(B1, 1, 1); PG8_SCHED; PG8_LDA(At, 1, 0); PG8_STAGE(PG8_SA(0, 1), a2 + hstepA, voffA);
;             PG8_WAIT_V(8); PG8_WAIT_L(0); PG8_BAR; PG8_MMA(0, 0, At, B0); PG8_MMA(0, 1, At, B1); PG8_BAR; PG8_SCHED;
;             PG8_LDA(At, 1, 1); PG8_STAGE(PG8_SB(1, 0), b3, voffB); PG8_STAGE(PG8_SB(1, 1), b3 + hstepB, voffB); PG8_STAGE(PG8_SA(1, 0), a3, voffA);
;             PG8_WAIT_V(8); PG8_WAIT_L(0); PG8_BAR; PG8_MMA(1, 0, At, B0); PG8_MMA(1, 1, At, B1); PG8_BAR; PG8_SCHED;
.LBB0_271:
	v_add_u32_e32 v0, 0x10000, v179
	ds_read_b128 v[130:133], v0
	ds_read_b128 v[134:137], v0 offset:1024
	ds_read_b128 v[138:141], v0 offset:2048
	ds_read_b128 v[142:145], v0 offset:3072
	v_add_u32_e32 v0, 0x14000, v179
	ds_read_b128 v[146:149], v0
	ds_read_b128 v[150:153], v0 offset:1024
	ds_read_b128 v[154:157], v0 offset:2048
	ds_read_b128 v[158:161], v0 offset:3072
	s_add_i32 s55, s44, 2
	s_add_u32 s45, s0, 0xfffc0080
	s_addc_u32 s56, s1, -1
	s_cmp_eq_u32 s68, s44
	s_cselect_b32 s60, s96, s45
	s_cselect_b32 s61, s97, s56
	s_cselect_b32 s58, s48, s4
	s_cselect_b32 s59, s49, s5
	s_add_u32 s56, s60, 0x80
	s_addc_u32 s57, s61, 0
	ds_read_b128 v[182:185], v180
	ds_read_b128 v[186:189], v180 offset:1024
	ds_read_b128 v[190:193], v180 offset:2048
	ds_read_b128 v[202:205], v180 offset:3072
	ds_read_b128 v[206:209], v180 offset:4096
	ds_read_b128 v[210:213], v180 offset:5120
	ds_read_b128 v[214:217], v180 offset:6144
	ds_read_b128 v[240:243], v180 offset:7168
	s_mov_b32 m0, s41
	s_nop 0
	global_load_lds_dwordx4 v165, s[0:1]
	s_nop 0
	s_mov_b32 m0, s30
	s_nop 0
	global_load_lds_dwordx4 v171, s[0:1]
	s_waitcnt vmcnt(8)
	s_waitcnt lgkmcnt(0)
	s_barrier
	s_setprio 1
	s_waitcnt lgkmcnt(0)
	v_mfma_f32_16x16x32_bf16 v[126:129], v[130:133], v[182:185], v[126:129]
	v_mfma_f32_16x16x32_bf16 v[126:129], v[134:137], v[186:189], v[126:129]
	v_mfma_f32_16x16x32_bf16 v[122:125], v[138:141], v[182:185], v[122:125]
	v_mfma_f32_16x16x32_bf16 v[122:125], v[142:145], v[186:189], v[122:125]
	v_mfma_f32_16x16x32_bf16 v[118:121], v[146:149], v[182:185], v[118:121]
	v_mfma_f32_16x16x32_bf16 v[118:121], v[150:153], v[186:189], v[118:121]
	v_mfma_f32_16x16x32_bf16 v[110:113], v[154:157], v[182:185], v[110:113]
	v_mfma_f32_16x16x32_bf16 v[110:113], v[158:161], v[186:189], v[110:113]
	v_mfma_f32_16x16x32_bf16 v[94:97], v[154:157], v[190:193], v[94:97]
	v_mfma_f32_16x16x32_bf16 v[94:97], v[158:161], v[202:205], v[94:97]
	v_mfma_f32_16x16x32_bf16 v[102:105], v[146:149], v[190:193], v[102:105]
	v_mfma_f32_16x16x32_bf16 v[102:105], v[150:153], v[202:205], v[102:105]
	v_mfma_f32_16x16x32_bf16 v[106:109], v[138:141], v[190:193], v[106:109]
	v_mfma_f32_16x16x32_bf16 v[106:109], v[142:145], v[202:205], v[106:109]
	v_mfma_f32_16x16x32_bf16 v[114:117], v[130:133], v[190:193], v[114:117]
	v_mfma_f32_16x16x32_bf16 v[114:117], v[134:137], v[202:205], v[114:117]
	v_mfma_f32_16x16x32_bf16 v[98:101], v[130:133], v[206:209], v[98:101]
	v_mfma_f32_16x16x32_bf16 v[98:101], v[134:137], v[210:213], v[98:101]
	v_mfma_f32_16x16x32_bf16 v[90:93], v[138:141], v[206:209], v[90:93]
	v_mfma_f32_16x16x32_bf16 v[90:93], v[142:145], v[210:213], v[90:93]
	v_mfma_f32_16x16x32_bf16 v[86:89], v[146:149], v[206:209], v[86:89]
	v_mfma_f32_16x16x32_bf16 v[86:89], v[150:153], v[210:213], v[86:89]
	v_mfma_f32_16x16x32_bf16 v[78:81], v[154:157], v[206:209], v[78:81]
	v_mfma_f32_16x16x32_bf16 v[78:81], v[158:161], v[210:213], v[78:81]
	v_mfma_f32_16x16x32_bf16 v[66:69], v[154:157], v[214:217], v[66:69]
	v_mfma_f32_16x16x32_bf16 v[66:69], v[158:161], v[240:243], v[66:69]
	v_mfma_f32_16x16x32_bf16 v[70:73], v[146:149], v[214:217], v[70:73]
	v_mfma_f32_16x16x32_bf16 v[70:73], v[150:153], v[240:243], v[70:73]
	v_mfma_f32_16x16x32_bf16 v[74:77], v[138:141], v[214:217], v[74:77]
	v_mfma_f32_16x16x32_bf16 v[74:77], v[142:145], v[240:243], v[74:77]
	v_mfma_f32_16x16x32_bf16 v[82:85], v[130:133], v[214:217], v[82:85]
	v_mfma_f32_16x16x32_bf16 v[82:85], v[134:137], v[240:243], v[82:85]
	s_setprio 0
	s_barrier
	ds_read_b128 v[182:185], v180 offset:16384
	ds_read_b128 v[186:189], v180 offset:17408
	ds_read_b128 v[190:193], v180 offset:18432
	ds_read_b128 v[202:205], v180 offset:19456
	ds_read_b128 v[206:209], v180 offset:20480
	ds_read_b128 v[210:213], v180 offset:21504
	ds_read_b128 v[214:217], v180 offset:22528
	ds_read_b128 v[240:243], v180 offset:23552
	s_mov_b32 m0, s42
	s_nop 0
	global_load_lds_dwordx4 v167, s[58:59]
	s_add_u32 s44, s58, s14
	s_mov_b32 m0, s43
	s_nop 0
	global_load_lds_dwordx4 v175, s[58:59]
	s_addc_u32 s45, s59, 0
	s_mov_b32 m0, s46
	s_nop 0
	global_load_lds_dwordx4 v167, s[44:45]
	s_nop 0
	s_mov_b32 m0, s50
	s_nop 0
	global_load_lds_dwordx4 v175, s[44:45]
	s_nop 0
	s_mov_b32 m0, s17
	s_nop 0
	global_load_lds_dwordx4 v165, s[60:61]
	s_nop 0
	s_mov_b32 m0, s53
	s_nop 0
	global_load_lds_dwordx4 v171, s[60:61]
	s_waitcnt vmcnt(8)
	s_waitcnt lgkmcnt(0)
	s_barrier
	s_setprio 1
	s_waitcnt lgkmcnt(0)
	v_mfma_f32_16x16x32_bf16 v[62:65], v[130:133], v[182:185], v[62:65]
	v_mfma_f32_16x16x32_bf16 v[62:65], v[134:137], v[186:189], v[62:65]
	v_mfma_f32_16x16x32_bf16 v[58:61], v[138:141], v[182:185], v[58:61]
	v_mfma_f32_16x16x32_bf16 v[58:61], v[142:145], v[186:189], v[58:61]
	v_mfma_f32_16x16x32_bf16 v[54:57], v[146:149], v[182:185], v[54:57]
	v_mfma_f32_16x16x32_bf16 v[54:57], v[150:153], v[186:189], v[54:57]
	v_mfma_f32_16x16x32_bf16 v[50:53], v[154:157], v[182:185], v[50:53]
	v_mfma_f32_16x16x32_bf16 v[50:53], v[158:161], v[186:189], v[50:53]
	v_mfma_f32_16x16x32_bf16 v[30:33], v[154:157], v[190:193], v[30:33]
	v_mfma_f32_16x16x32_bf16 v[30:33], v[158:161], v[202:205], v[30:33]
	v_mfma_f32_16x16x32_bf16 v[38:41], v[146:149], v[190:193], v[38:41]
	v_mfma_f32_16x16x32_bf16 v[38:41], v[150:153], v[202:205], v[38:41]
	v_mfma_f32_16x16x32_bf16 v[42:45], v[138:141], v[190:193], v[42:45]
	v_mfma_f32_16x16x32_bf16 v[42:45], v[142:145], v[202:205], v[42:45]
	v_mfma_f32_16x16x32_bf16 v[46:49], v[130:133], v[190:193], v[46:49]
	v_mfma_f32_16x16x32_bf16 v[46:49], v[134:137], v[202:205], v[46:49]
	v_mfma_f32_16x16x32_bf16 v[34:37], v[130:133], v[206:209], v[34:37]
	v_mfma_f32_16x16x32_bf16 v[34:37], v[134:137], v[210:213], v[34:37]
	v_mfma_f32_16x16x32_bf16 v[26:29], v[138:141], v[206:209], v[26:29]
	v_mfma_f32_16x16x32_bf16 v[26:29], v[142:145], v[210:213], v[26:29]
	v_mfma_f32_16x16x32_bf16 v[22:25], v[146:149], v[206:209], v[22:25]
	v_mfma_f32_16x16x32_bf16 v[22:25], v[150:153], v[210:213], v[22:25]
	v_mfma_f32_16x16x32_bf16 v[14:17], v[154:157], v[206:209], v[14:17]
	v_mfma_f32_16x16x32_bf16 v[14:17], v[158:161], v[210:213], v[14:17]
	v_mfma_f32_16x16x32_bf16 v[2:5], v[154:157], v[214:217], v[2:5]
	v_mfma_f32_16x16x32_bf16 v[2:5], v[158:161], v[240:243], v[2:5]
	v_mfma_f32_16x16x32_bf16 v[6:9], v[146:149], v[214:217], v[6:9]
	v_mfma_f32_16x16x32_bf16 v[6:9], v[150:153], v[240:243], v[6:9]
	v_mfma_f32_16x16x32_bf16 v[10:13], v[138:141], v[214:217], v[10:13]
	v_mfma_f32_16x16x32_bf16 v[10:13], v[142:145], v[240:243], v[10:13]
	v_mfma_f32_16x16x32_bf16 v[18:21], v[130:133], v[214:217], v[18:21]
	v_mfma_f32_16x16x32_bf16 v[18:21], v[134:137], v[240:243], v[18:21]
	s_setprio 0
	s_barrier
; #define PG8_STAGE(bufoff, gbase, voff) do { _Pragma("unroll") for (int _i = 0; _i < 2; ++_i) { \
;         const unsigned _m0 = ldsb + (unsigned)((bufoff) + _i * 8192); const char* _gb = (const char*)(gbase); \
;         asm volatile("s_mov_b32 m0, %0\n\ts_nop 0\n\tglobal_load_lds_dwordx4 %1, %2" :: "s"(_m0), "v"((voff)[_i]), "s"(_gb) : "m0", "memory"); } } while (0)
; #define PG8_LDA(dst, b, h) do { _Pragma("unroll") for (int m = 0; m < 4; ++m) _Pragma("unroll") for (int k = 0; k < 2; ++k) dst[m][k] = *(const LAS bf16x8*)(lds + PG8_SA(b, h) + aoff + m * 2048 + k * 1024); } while (0)
; #define PG8_LDB(dst, b, h) do { _Pragma("unroll") for (int n = 0; n < 2; ++n) _Pragma("unroll") for (int k = 0; k < 2; ++k) dst[n][k] = *(const LAS bf16x8*)(lds + PG8_SB(b, h) + boff + n * 2048 + k * 1024); } while (0)
; #define PG8_MMA(ai, bj, At, Bt) do { __builtin_amdgcn_s_setprio(1); _Pragma("unroll") for (int m = 0; m < 4; ++m) _Pragma("unroll") for (int n = 0; n < 2; ++n) _Pragma("unroll") for (int k = 0; k < 2; ++k) \
;         acc[ai][bj][m][n] = __builtin_amdgcn_mfma_f32_16x16x32_bf16(Bt[n][k], At[m][k], acc[ai][bj][m][n], 0, 0, 0); __builtin_amdgcn_s_setprio(0); } while (0)
; template <class Epi, bool ALIGN_EPI>
; __device__ __forceinline__ void gemm_phase(LAS unsigned char* lds, const Gemm g, const StaticOrder& S, const Epi& E) {
;     ...
;             PG8_LDB(B0, 0, 0); PG8_LDB(B1, 0, 1); PG8_SCHED; PG8_LDA(At, 0, 0); PG8_STAGE(PG8_SA(1, 1), a1 + hstepA, voffA);
;             PG8_WAIT_V(8); PG8_WAIT_L(0); PG8_BAR; PG8_MMA(0, 0, At, B0); PG8_MMA(0, 1, At, B1); PG8_BAR; PG8_SCHED;
;             PG8_LDA(At, 0, 1); PG8_STAGE(PG8_SB(0, 0), b2, voffB); PG8_STAGE(PG8_SB(0, 1), b2 + hstepB, voffB); PG8_STAGE(PG8_SA(0, 0), a2, voffA);
;             PG8_WAIT_V(8); PG8_WAIT_L(0); PG8_BAR; PG8_MMA(1, 0, At, B0); PG8_MMA(1, 1, At, B1); PG8_BAR; PG8_SCHED;
;             PG8_LDB(B0, 1, 0); PG8_LDB(B1, 1, 1); PG8_SCHED; PG8_LDA(At, 1, 0); PG8_STAGE(PG8_SA(0, 1), a2 + hstepA, voffA);
;             PG8_WAIT_V(8); PG8_WAIT_L(0); PG8_BAR; PG8_MMA(0, 0, At, B0); PG8_MMA(0, 1, At, B1); PG8_BAR; PG8_SCHED;
;             PG8_LDA(At, 1, 1); PG8_STAGE(PG8_SB(1, 0), b3, voffB); PG8_STAGE(PG8_SB(1, 1), b3 + hstepB, voffB); PG8_STAGE(PG8_SA(1, 0), a3, voffA);
;             PG8_WAIT_V(8); PG8_WAIT_L(0); PG8_BAR; PG8_MMA(1, 0, At, B0); PG8_MMA(1, 1, At, B1); PG8_BAR; PG8_SCHED;
	v_add_u32_e32 v0, 0x18000, v179
	ds_read_b128 v[130:133], v0
	ds_read_b128 v[134:137], v0 offset:1024
	ds_read_b128 v[138:141], v0 offset:2048
	ds_read_b128 v[142:145], v0 offset:3072
	v_add_u32_e32 v0, 0x1c000, v179
	ds_read_b128 v[146:149], v0
	ds_read_b128 v[150:153], v0 offset:1024
	ds_read_b128 v[154:157], v0 offset:2048
	ds_read_b128 v[158:161], v0 offset:3072
	ds_read_b128 v[182:185], v180 offset:32768
	ds_read_b128 v[186:189], v180 offset:33792
	ds_read_b128 v[190:193], v180 offset:34816
	ds_read_b128 v[202:205], v180 offset:35840
	ds_read_b128 v[206:209], v180 offset:36864
	ds_read_b128 v[210:213], v180 offset:37888
	ds_read_b128 v[214:217], v180 offset:38912
	ds_read_b128 v[240:243], v180 offset:39936
	s_add_u32 s60, s60, 0x40000
	s_addc_u32 s61, s61, 0
	s_mov_b32 m0, s65
	s_nop 0
	global_load_lds_dwordx4 v165, s[60:61]
	s_nop 0
	s_mov_b32 m0, s67
	s_nop 0
	global_load_lds_dwordx4 v171, s[60:61]
	s_waitcnt vmcnt(8)
	s_waitcnt lgkmcnt(0)
	s_barrier
	s_setprio 1
	s_waitcnt lgkmcnt(0)
	v_mfma_f32_16x16x32_bf16 v[126:129], v[130:133], v[182:185], v[126:129]
	v_mfma_f32_16x16x32_bf16 v[126:129], v[134:137], v[186:189], v[126:129]
	v_mfma_f32_16x16x32_bf16 v[122:125], v[138:141], v[182:185], v[122:125]
	v_mfma_f32_16x16x32_bf16 v[122:125], v[142:145], v[186:189], v[122:125]
	v_mfma_f32_16x16x32_bf16 v[118:121], v[146:149], v[182:185], v[118:121]
	v_mfma_f32_16x16x32_bf16 v[118:121], v[150:153], v[186:189], v[118:121]
	v_mfma_f32_16x16x32_bf16 v[110:113], v[154:157], v[182:185], v[110:113]
	v_mfma_f32_16x16x32_bf16 v[110:113], v[158:161], v[186:189], v[110:113]
	v_mfma_f32_16x16x32_bf16 v[94:97], v[154:157], v[190:193], v[94:97]
	v_mfma_f32_16x16x32_bf16 v[94:97], v[158:161], v[202:205], v[94:97]
	v_mfma_f32_16x16x32_bf16 v[102:105], v[146:149], v[190:193], v[102:105]
	v_mfma_f32_16x16x32_bf16 v[102:105], v[150:153], v[202:205], v[102:105]
	v_mfma_f32_16x16x32_bf16 v[106:109], v[138:141], v[190:193], v[106:109]
	v_mfma_f32_16x16x32_bf16 v[106:109], v[142:145], v[202:205], v[106:109]
	v_mfma_f32_16x16x32_bf16 v[114:117], v[130:133], v[190:193], v[114:117]
	v_mfma_f32_16x16x32_bf16 v[114:117], v[134:137], v[202:205], v[114:117]
	v_mfma_f32_16x16x32_bf16 v[98:101], v[130:133], v[206:209], v[98:101]
	v_mfma_f32_16x16x32_bf16 v[98:101], v[134:137], v[210:213], v[98:101]
	v_mfma_f32_16x16x32_bf16 v[90:93], v[138:141], v[206:209], v[90:93]
	v_mfma_f32_16x16x32_bf16 v[90:93], v[142:145], v[210:213], v[90:93]
	v_mfma_f32_16x16x32_bf16 v[86:89], v[146:149], v[206:209], v[86:89]
	v_mfma_f32_16x16x32_bf16 v[86:89], v[150:153], v[210:213], v[86:89]
	v_mfma_f32_16x16x32_bf16 v[78:81], v[154:157], v[206:209], v[78:81]
	v_mfma_f32_16x16x32_bf16 v[78:81], v[158:161], v[210:213], v[78:81]
	v_mfma_f32_16x16x32_bf16 v[66:69], v[154:157], v[214:217], v[66:69]
	v_mfma_f32_16x16x32_bf16 v[66:69], v[158:161], v[240:243], v[66:69]
	v_mfma_f32_16x16x32_bf16 v[70:73], v[146:149], v[214:217], v[70:73]
	v_mfma_f32_16x16x32_bf16 v[70:73], v[150:153], v[240:243], v[70:73]
	v_mfma_f32_16x16x32_bf16 v[74:77], v[138:141], v[214:217], v[74:77]
	v_mfma_f32_16x16x32_bf16 v[74:77], v[142:145], v[240:243], v[74:77]
	v_mfma_f32_16x16x32_bf16 v[82:85], v[130:133], v[214:217], v[82:85]
	v_mfma_f32_16x16x32_bf16 v[82:85], v[134:137], v[240:243], v[82:85]
	s_setprio 0
	s_barrier
	ds_read_b128 v[182:185], v180 offset:49152
	ds_read_b128 v[186:189], v180 offset:50176
	ds_read_b128 v[190:193], v180 offset:51200
	ds_read_b128 v[202:205], v180 offset:52224
	ds_read_b128 v[206:209], v180 offset:53248
	ds_read_b128 v[210:213], v180 offset:54272
	ds_read_b128 v[214:217], v180 offset:55296
	ds_read_b128 v[240:243], v180 offset:56320
	s_add_u32 s58, s58, 0x80
	s_addc_u32 s59, s59, 0
	s_mov_b32 m0, s89
	s_nop 0
	global_load_lds_dwordx4 v167, s[58:59]
	s_add_u32 s44, s44, 0x80
	s_mov_b32 m0, s95
	s_nop 0
	global_load_lds_dwordx4 v175, s[58:59]
	s_addc_u32 s45, s45, 0
	s_mov_b32 m0, s26
	s_nop 0
	global_load_lds_dwordx4 v167, s[44:45]
	s_nop 0
	s_mov_b32 m0, s27
	s_nop 0
	global_load_lds_dwordx4 v175, s[44:45]
	s_nop 0
	s_mov_b32 m0, s36
	s_nop 0
	global_load_lds_dwordx4 v165, s[56:57]
	s_nop 0
	s_mov_b32 m0, s37
	s_nop 0
	global_load_lds_dwordx4 v171, s[56:57]
	s_waitcnt vmcnt(8)
	s_waitcnt lgkmcnt(0)
	s_barrier
	s_setprio 1
	s_waitcnt lgkmcnt(0)
	v_mfma_f32_16x16x32_bf16 v[62:65], v[130:133], v[182:185], v[62:65]
	v_mfma_f32_16x16x32_bf16 v[62:65], v[134:137], v[186:189], v[62:65]
	v_mfma_f32_16x16x32_bf16 v[58:61], v[138:141], v[182:185], v[58:61]
	v_mfma_f32_16x16x32_bf16 v[58:61], v[142:145], v[186:189], v[58:61]
	v_mfma_f32_16x16x32_bf16 v[54:57], v[146:149], v[182:185], v[54:57]
	v_mfma_f32_16x16x32_bf16 v[54:57], v[150:153], v[186:189], v[54:57]
	v_mfma_f32_16x16x32_bf16 v[50:53], v[154:157], v[182:185], v[50:53]
	v_mfma_f32_16x16x32_bf16 v[50:53], v[158:161], v[186:189], v[50:53]
	v_mfma_f32_16x16x32_bf16 v[30:33], v[154:157], v[190:193], v[30:33]
	v_mfma_f32_16x16x32_bf16 v[30:33], v[158:161], v[202:205], v[30:33]
	v_mfma_f32_16x16x32_bf16 v[38:41], v[146:149], v[190:193], v[38:41]
	v_mfma_f32_16x16x32_bf16 v[38:41], v[150:153], v[202:205], v[38:41]
	v_mfma_f32_16x16x32_bf16 v[42:45], v[138:141], v[190:193], v[42:45]
	v_mfma_f32_16x16x32_bf16 v[42:45], v[142:145], v[202:205], v[42:45]
	v_mfma_f32_16x16x32_bf16 v[46:49], v[130:133], v[190:193], v[46:49]
	v_mfma_f32_16x16x32_bf16 v[46:49], v[134:137], v[202:205], v[46:49]
	v_mfma_f32_16x16x32_bf16 v[34:37], v[130:133], v[206:209], v[34:37]
	v_mfma_f32_16x16x32_bf16 v[34:37], v[134:137], v[210:213], v[34:37]
	v_mfma_f32_16x16x32_bf16 v[26:29], v[138:141], v[206:209], v[26:29]
	v_mfma_f32_16x16x32_bf16 v[26:29], v[142:145], v[210:213], v[26:29]
	v_mfma_f32_16x16x32_bf16 v[22:25], v[146:149], v[206:209], v[22:25]
	v_mfma_f32_16x16x32_bf16 v[22:25], v[150:153], v[210:213], v[22:25]
	v_mfma_f32_16x16x32_bf16 v[14:17], v[154:157], v[206:209], v[14:17]
	v_mfma_f32_16x16x32_bf16 v[14:17], v[158:161], v[210:213], v[14:17]
	v_mfma_f32_16x16x32_bf16 v[2:5], v[154:157], v[214:217], v[2:5]
	v_mfma_f32_16x16x32_bf16 v[2:5], v[158:161], v[240:243], v[2:5]
	v_mfma_f32_16x16x32_bf16 v[6:9], v[146:149], v[214:217], v[6:9]
	v_mfma_f32_16x16x32_bf16 v[6:9], v[150:153], v[240:243], v[6:9]
	v_mfma_f32_16x16x32_bf16 v[10:13], v[138:141], v[214:217], v[10:13]
	v_mfma_f32_16x16x32_bf16 v[10:13], v[142:145], v[240:243], v[10:13]
	v_mfma_f32_16x16x32_bf16 v[18:21], v[130:133], v[214:217], v[18:21]
	v_mfma_f32_16x16x32_bf16 v[18:21], v[134:137], v[240:243], v[18:21]
	s_setprio 0
	s_barrier
	s_add_u32 s4, s4, 0x100
	s_addc_u32 s5, s5, 0
	s_add_u32 s0, s0, 0x100
	s_addc_u32 s1, s1, 0
	s_cmp_ge_u32 s55, s31
	s_mov_b32 s44, s55
	s_cbranch_scc0 .LBB0_271
	v_readlane_b32 s0, v254, 44
	v_readlane_b32 s1, v254, 45
	s_and_b64 vcc, exec, s[0:1]
	s_cbranch_vccz .LBB0_274
	s_barrier

; #define PG8_STAGE(bufoff, gbase, voff) do { _Pragma("unroll") for (int _i = 0; _i < 2; ++_i) { \
;         const unsigned _m0 = ldsb + (unsigned)((bufoff) + _i * 8192); const char* _gb = (const char*)(gbase); \
;         asm volatile("s_mov_b32 m0, %0\n\ts_nop 0\n\tglobal_load_lds_dwordx4 %1, %2" :: "s"(_m0), "v"((voff)[_i]), "s"(_gb) : "m0", "memory"); } } while (0)
; #define PG8_LDA(dst, b, h) do { _Pragma("unroll") for (int m = 0; m < 4; ++m) _Pragma("unroll") for (int k = 0; k < 2; ++k) dst[m][k] = *(const LAS bf16x8*)(lds + PG8_SA(b, h) + aoff + m * 2048 + k * 1024); } while (0)
; #define PG8_LDB(dst, b, h) do { _Pragma("unroll") for (int n = 0; n < 2; ++n) _Pragma("unroll") for (int k = 0; k < 2; ++k) dst[n][k] = *(const LAS bf16x8*)(lds + PG8_SB(b, h) + boff + n * 2048 + k * 1024); } while (0)
; #define PG8_MMA(ai, bj, At, Bt) do { __builtin_amdgcn_s_setprio(1); _Pragma("unroll") for (int m = 0; m < 4; ++m) _Pragma("unroll") for (int n = 0; n < 2; ++n) _Pragma("unroll") for (int k = 0; k < 2; ++k) \
;         acc[ai][bj][m][n] = __builtin_amdgcn_mfma_f32_16x16x32_bf16(Bt[n][k], At[m][k], acc[ai][bj][m][n], 0, 0, 0); __builtin_amdgcn_s_setprio(0); } while (0)
; template <class Epi, bool ALIGN_EPI>
; __device__ __forceinline__ void gemm_phase(LAS unsigned char* lds, const Gemm g, const StaticOrder& S, const Epi& E) {
;     ...
;             PG8_LDB(B0, 0, 0); PG8_LDB(B1, 0, 1); PG8_SCHED; PG8_LDA(At, 0, 0); PG8_STAGE(PG8_SA(1, 1), a1 + hstepA, voffA);
;             PG8_WAIT_V(8); PG8_WAIT_L(0); PG8_BAR; PG8_MMA(0, 0, At, B0); PG8_MMA(0, 1, At, B1); PG8_BAR; PG8_SCHED;
;             PG8_LDA(At, 0, 1); PG8_STAGE(PG8_SB(0, 0), b2, voffB); PG8_STAGE(PG8_SB(0, 1), b2 + hstepB, voffB); PG8_STAGE(PG8_SA(0, 0), a2, voffA);
;             PG8_WAIT_V(8); PG8_WAIT_L(0); PG8_BAR; PG8_MMA(1, 0, At, B0); PG8_MMA(1, 1, At, B1); PG8_BAR; PG8_SCHED;
;             PG8_LDB(B0, 1, 0); PG8_LDB(B1, 1, 1); PG8_SCHED; PG8_LDA(At, 1, 0); PG8_STAGE(PG8_SA(0, 1), a2 + hstepA, voffA);
;             PG8_WAIT_V(8); PG8_WAIT_L(0); PG8_BAR; PG8_MMA(0, 0, At, B0); PG8_MMA(0, 1, At, B1); PG8_BAR; PG8_SCHED;
;             PG8_LDA(At, 1, 1); PG8_STAGE(PG8_SB(1, 0), b3, voffB); PG8_STAGE(PG8_SB(1, 1), b3 + hstepB, voffB); PG8_STAGE(PG8_SA(1, 0), a3, voffA);
;             PG8_WAIT_V(8); PG8_WAIT_L(0); PG8_BAR; PG8_MMA(1, 0, At, B0); PG8_MMA(1, 1, At, B1); PG8_BAR; PG8_SCHED;
.LBB0_306:
	v_add_u32_e32 v134, 0x10000, v185
	v_add_u32_e32 v158, 0x14000, v185
	ds_read_b128 v[74:77], v134
	ds_read_b128 v[94:97], v134 offset:1024
	ds_read_b128 v[114:117], v134 offset:2048
	ds_read_b128 v[134:137], v134 offset:3072
	ds_read_b128 v[146:149], v158
	ds_read_b128 v[150:153], v158 offset:1024
	ds_read_b128 v[154:157], v158 offset:2048
	ds_read_b128 v[158:161], v158 offset:3072
	s_add_u32 s30, s92, 0xfffc0080
	s_addc_u32 s31, s93, -1
	s_cmp_eq_u32 s50, 12
	s_cselect_b32 s60, s5, s30
	s_cselect_b32 s61, s4, s31
	s_cselect_b32 s58, s37, s41
	s_cselect_b32 s59, s35, s49
	s_add_u32 s56, s60, 0x80
	s_addc_u32 s57, s61, 0
	ds_read_b128 v[162:165], v186
	ds_read_b128 v[166:169], v186 offset:1024
	ds_read_b128 v[170:173], v186 offset:2048
	ds_read_b128 v[174:177], v186 offset:3072
	ds_read_b128 v[188:191], v186 offset:4096
	ds_read_b128 v[202:205], v186 offset:5120
	ds_read_b128 v[206:209], v186 offset:6144
	ds_read_b128 v[210:213], v186 offset:7168
	s_mov_b32 m0, s67
	s_nop 0
	global_load_lds_dwordx4 v0, s[92:93]
	s_nop 0
	s_mov_b32 m0, s65
	s_nop 0
	global_load_lds_dwordx4 v181, s[92:93]
	s_waitcnt vmcnt(8)
	s_waitcnt lgkmcnt(0)
	s_barrier
	s_setprio 1
	s_waitcnt lgkmcnt(0)
	v_mfma_f32_16x16x32_bf16 v[142:145], v[74:77], v[162:165], v[142:145]
	v_mfma_f32_16x16x32_bf16 v[142:145], v[94:97], v[166:169], v[142:145]
	v_mfma_f32_16x16x32_bf16 v[138:141], v[114:117], v[162:165], v[138:141]
	v_mfma_f32_16x16x32_bf16 v[138:141], v[134:137], v[166:169], v[138:141]
	v_mfma_f32_16x16x32_bf16 v[130:133], v[146:149], v[162:165], v[130:133]
	v_mfma_f32_16x16x32_bf16 v[130:133], v[150:153], v[166:169], v[130:133]
	v_mfma_f32_16x16x32_bf16 v[126:129], v[154:157], v[162:165], v[126:129]
	v_mfma_f32_16x16x32_bf16 v[126:129], v[158:161], v[166:169], v[126:129]
	v_mfma_f32_16x16x32_bf16 v[106:109], v[154:157], v[170:173], v[106:109]
	v_mfma_f32_16x16x32_bf16 v[106:109], v[158:161], v[174:177], v[106:109]
	v_mfma_f32_16x16x32_bf16 v[110:113], v[146:149], v[170:173], v[110:113]
	v_mfma_f32_16x16x32_bf16 v[110:113], v[150:153], v[174:177], v[110:113]
	v_mfma_f32_16x16x32_bf16 v[118:121], v[114:117], v[170:173], v[118:121]
	v_mfma_f32_16x16x32_bf16 v[118:121], v[134:137], v[174:177], v[118:121]
	v_mfma_f32_16x16x32_bf16 v[122:125], v[74:77], v[170:173], v[122:125]
	v_mfma_f32_16x16x32_bf16 v[122:125], v[94:97], v[174:177], v[122:125]
	v_mfma_f32_16x16x32_bf16 v[102:105], v[74:77], v[188:191], v[102:105]
	v_mfma_f32_16x16x32_bf16 v[102:105], v[94:97], v[202:205], v[102:105]
	v_mfma_f32_16x16x32_bf16 v[98:101], v[114:117], v[188:191], v[98:101]
	v_mfma_f32_16x16x32_bf16 v[98:101], v[134:137], v[202:205], v[98:101]
	v_mfma_f32_16x16x32_bf16 v[90:93], v[146:149], v[188:191], v[90:93]
	v_mfma_f32_16x16x32_bf16 v[90:93], v[150:153], v[202:205], v[90:93]
	v_mfma_f32_16x16x32_bf16 v[86:89], v[154:157], v[188:191], v[86:89]
	v_mfma_f32_16x16x32_bf16 v[86:89], v[158:161], v[202:205], v[86:89]
	v_mfma_f32_16x16x32_bf16 v[66:69], v[154:157], v[206:209], v[66:69]
	v_mfma_f32_16x16x32_bf16 v[66:69], v[158:161], v[210:213], v[66:69]
	v_mfma_f32_16x16x32_bf16 v[70:73], v[146:149], v[206:209], v[70:73]
	v_mfma_f32_16x16x32_bf16 v[70:73], v[150:153], v[210:213], v[70:73]
	v_mfma_f32_16x16x32_bf16 v[78:81], v[114:117], v[206:209], v[78:81]
	v_mfma_f32_16x16x32_bf16 v[78:81], v[134:137], v[210:213], v[78:81]
	v_mfma_f32_16x16x32_bf16 v[82:85], v[74:77], v[206:209], v[82:85]
	v_mfma_f32_16x16x32_bf16 v[82:85], v[94:97], v[210:213], v[82:85]
	s_setprio 0
	s_barrier
	ds_read_b128 v[162:165], v186 offset:16384
	ds_read_b128 v[166:169], v186 offset:17408
	ds_read_b128 v[170:173], v186 offset:18432
	ds_read_b128 v[174:177], v186 offset:19456
	ds_read_b128 v[188:191], v186 offset:20480
	ds_read_b128 v[202:205], v186 offset:21504
	ds_read_b128 v[206:209], v186 offset:22528
	ds_read_b128 v[210:213], v186 offset:23552
	s_mov_b32 m0, s29
	s_nop 0
	global_load_lds_dwordx4 v180, s[58:59]
	s_add_u32 s30, s58, 0x40000
	s_mov_b32 m0, s42
	s_nop 0
	global_load_lds_dwordx4 v182, s[58:59]
	s_addc_u32 s31, s59, 0
	s_mov_b32 m0, s43
	s_nop 0
	global_load_lds_dwordx4 v180, s[30:31]
	s_nop 0
	s_mov_b32 m0, s44
	s_nop 0
	global_load_lds_dwordx4 v182, s[30:31]
	s_nop 0
	s_mov_b32 m0, s15
	s_nop 0
	global_load_lds_dwordx4 v0, s[60:61]
	s_nop 0
	s_mov_b32 m0, s45
	s_nop 0
	global_load_lds_dwordx4 v181, s[60:61]
	s_waitcnt vmcnt(8)
	s_waitcnt lgkmcnt(0)
	s_barrier
	s_setprio 1
	s_waitcnt lgkmcnt(0)
	v_mfma_f32_16x16x32_bf16 v[62:65], v[74:77], v[162:165], v[62:65]
	v_mfma_f32_16x16x32_bf16 v[62:65], v[94:97], v[166:169], v[62:65]
	v_mfma_f32_16x16x32_bf16 v[58:61], v[114:117], v[162:165], v[58:61]
	v_mfma_f32_16x16x32_bf16 v[58:61], v[134:137], v[166:169], v[58:61]
	v_mfma_f32_16x16x32_bf16 v[54:57], v[146:149], v[162:165], v[54:57]
	v_mfma_f32_16x16x32_bf16 v[54:57], v[150:153], v[166:169], v[54:57]
	v_mfma_f32_16x16x32_bf16 v[50:53], v[154:157], v[162:165], v[50:53]
	v_mfma_f32_16x16x32_bf16 v[50:53], v[158:161], v[166:169], v[50:53]
	v_mfma_f32_16x16x32_bf16 v[34:37], v[154:157], v[170:173], v[34:37]
	v_mfma_f32_16x16x32_bf16 v[34:37], v[158:161], v[174:177], v[34:37]
	v_mfma_f32_16x16x32_bf16 v[38:41], v[146:149], v[170:173], v[38:41]
	v_mfma_f32_16x16x32_bf16 v[38:41], v[150:153], v[174:177], v[38:41]
	v_mfma_f32_16x16x32_bf16 v[42:45], v[114:117], v[170:173], v[42:45]
	v_mfma_f32_16x16x32_bf16 v[42:45], v[134:137], v[174:177], v[42:45]
	v_mfma_f32_16x16x32_bf16 v[46:49], v[74:77], v[170:173], v[46:49]
	v_mfma_f32_16x16x32_bf16 v[46:49], v[94:97], v[174:177], v[46:49]
	v_mfma_f32_16x16x32_bf16 v[30:33], v[74:77], v[188:191], v[30:33]
	v_mfma_f32_16x16x32_bf16 v[30:33], v[94:97], v[202:205], v[30:33]
	v_mfma_f32_16x16x32_bf16 v[26:29], v[114:117], v[188:191], v[26:29]
	v_mfma_f32_16x16x32_bf16 v[26:29], v[134:137], v[202:205], v[26:29]
	v_mfma_f32_16x16x32_bf16 v[22:25], v[146:149], v[188:191], v[22:25]
	v_mfma_f32_16x16x32_bf16 v[22:25], v[150:153], v[202:205], v[22:25]
	v_mfma_f32_16x16x32_bf16 v[18:21], v[154:157], v[188:191], v[18:21]
	v_mfma_f32_16x16x32_bf16 v[18:21], v[158:161], v[202:205], v[18:21]
	v_mfma_f32_16x16x32_bf16 v[2:5], v[154:157], v[206:209], v[2:5]
	v_mfma_f32_16x16x32_bf16 v[2:5], v[158:161], v[210:213], v[2:5]
	v_mfma_f32_16x16x32_bf16 v[6:9], v[146:149], v[206:209], v[6:9]
	v_mfma_f32_16x16x32_bf16 v[6:9], v[150:153], v[210:213], v[6:9]
	v_mfma_f32_16x16x32_bf16 v[10:13], v[114:117], v[206:209], v[10:13]
	v_mfma_f32_16x16x32_bf16 v[10:13], v[134:137], v[210:213], v[10:13]
	v_mfma_f32_16x16x32_bf16 v[14:17], v[74:77], v[206:209], v[14:17]
	v_mfma_f32_16x16x32_bf16 v[14:17], v[94:97], v[210:213], v[14:17]
	s_setprio 0
	s_barrier
; #define PG8_STAGE(bufoff, gbase, voff) do { _Pragma("unroll") for (int _i = 0; _i < 2; ++_i) { \
;         const unsigned _m0 = ldsb + (unsigned)((bufoff) + _i * 8192); const char* _gb = (const char*)(gbase); \
;         asm volatile("s_mov_b32 m0, %0\n\ts_nop 0\n\tglobal_load_lds_dwordx4 %1, %2" :: "s"(_m0), "v"((voff)[_i]), "s"(_gb) : "m0", "memory"); } } while (0)
; #define PG8_LDA(dst, b, h) do { _Pragma("unroll") for (int m = 0; m < 4; ++m) _Pragma("unroll") for (int k = 0; k < 2; ++k) dst[m][k] = *(const LAS bf16x8*)(lds + PG8_SA(b, h) + aoff + m * 2048 + k * 1024); } while (0)
; #define PG8_LDB(dst, b, h) do { _Pragma("unroll") for (int n = 0; n < 2; ++n) _Pragma("unroll") for (int k = 0; k < 2; ++k) dst[n][k] = *(const LAS bf16x8*)(lds + PG8_SB(b, h) + boff + n * 2048 + k * 1024); } while (0)
; #define PG8_MMA(ai, bj, At, Bt) do { __builtin_amdgcn_s_setprio(1); _Pragma("unroll") for (int m = 0; m < 4; ++m) _Pragma("unroll") for (int n = 0; n < 2; ++n) _Pragma("unroll") for (int k = 0; k < 2; ++k) \
;         acc[ai][bj][m][n] = __builtin_amdgcn_mfma_f32_16x16x32_bf16(Bt[n][k], At[m][k], acc[ai][bj][m][n], 0, 0, 0); __builtin_amdgcn_s_setprio(0); } while (0)
; template <class Epi, bool ALIGN_EPI>
; __device__ __forceinline__ void gemm_phase(LAS unsigned char* lds, const Gemm g, const StaticOrder& S, const Epi& E) {
;     ...
;             PG8_LDB(B0, 0, 0); PG8_LDB(B1, 0, 1); PG8_SCHED; PG8_LDA(At, 0, 0); PG8_STAGE(PG8_SA(1, 1), a1 + hstepA, voffA);
;             PG8_WAIT_V(8); PG8_WAIT_L(0); PG8_BAR; PG8_MMA(0, 0, At, B0); PG8_MMA(0, 1, At, B1); PG8_BAR; PG8_SCHED;
;             PG8_LDA(At, 0, 1); PG8_STAGE(PG8_SB(0, 0), b2, voffB); PG8_STAGE(PG8_SB(0, 1), b2 + hstepB, voffB); PG8_STAGE(PG8_SA(0, 0), a2, voffA);
;             PG8_WAIT_V(8); PG8_WAIT_L(0); PG8_BAR; PG8_MMA(1, 0, At, B0); PG8_MMA(1, 1, At, B1); PG8_BAR; PG8_SCHED;
;             PG8_LDB(B0, 1, 0); PG8_LDB(B1, 1, 1); PG8_SCHED; PG8_LDA(At, 1, 0); PG8_STAGE(PG8_SA(0, 1), a2 + hstepA, voffA);
;             PG8_WAIT_V(8); PG8_WAIT_L(0); PG8_BAR; PG8_MMA(0, 0, At, B0); PG8_MMA(0, 1, At, B1); PG8_BAR; PG8_SCHED;
;             PG8_LDA(At, 1, 1); PG8_STAGE(PG8_SB(1, 0), b3, voffB); PG8_STAGE(PG8_SB(1, 1), b3 + hstepB, voffB); PG8_STAGE(PG8_SA(1, 0), a3, voffA);
;             PG8_WAIT_V(8); PG8_WAIT_L(0); PG8_BAR; PG8_MMA(1, 0, At, B0); PG8_MMA(1, 1, At, B1); PG8_BAR; PG8_SCHED;
	v_add_u32_e32 v134, 0x18000, v185
	v_add_u32_e32 v158, 0x1c000, v185
	ds_read_b128 v[74:77], v134
	ds_read_b128 v[94:97], v134 offset:1024
	ds_read_b128 v[114:117], v134 offset:2048
	ds_read_b128 v[134:137], v134 offset:3072
	ds_read_b128 v[146:149], v158
	ds_read_b128 v[150:153], v158 offset:1024
	ds_read_b128 v[154:157], v158 offset:2048
	ds_read_b128 v[158:161], v158 offset:3072
	ds_read_b128 v[162:165], v186 offset:32768
	ds_read_b128 v[166:169], v186 offset:33792
	ds_read_b128 v[170:173], v186 offset:34816
	ds_read_b128 v[174:177], v186 offset:35840
	ds_read_b128 v[188:191], v186 offset:36864
	ds_read_b128 v[202:205], v186 offset:37888
	ds_read_b128 v[206:209], v186 offset:38912
	ds_read_b128 v[210:213], v186 offset:39936
	s_add_u32 s30, s60, 0x40000
	s_addc_u32 s31, s61, 0
	s_mov_b32 m0, s55
	s_nop 0
	global_load_lds_dwordx4 v0, s[30:31]
	s_nop 0
	s_mov_b32 m0, s88
	s_nop 0
	global_load_lds_dwordx4 v181, s[30:31]
	s_waitcnt vmcnt(8)
	s_waitcnt lgkmcnt(0)
	s_barrier
	s_setprio 1
	s_waitcnt lgkmcnt(0)
	v_mfma_f32_16x16x32_bf16 v[142:145], v[74:77], v[162:165], v[142:145]
	v_mfma_f32_16x16x32_bf16 v[142:145], v[94:97], v[166:169], v[142:145]
	v_mfma_f32_16x16x32_bf16 v[138:141], v[114:117], v[162:165], v[138:141]
	v_mfma_f32_16x16x32_bf16 v[138:141], v[134:137], v[166:169], v[138:141]
	v_mfma_f32_16x16x32_bf16 v[130:133], v[146:149], v[162:165], v[130:133]
	v_mfma_f32_16x16x32_bf16 v[130:133], v[150:153], v[166:169], v[130:133]
	v_mfma_f32_16x16x32_bf16 v[126:129], v[154:157], v[162:165], v[126:129]
	v_mfma_f32_16x16x32_bf16 v[126:129], v[158:161], v[166:169], v[126:129]
	v_mfma_f32_16x16x32_bf16 v[106:109], v[154:157], v[170:173], v[106:109]
	v_mfma_f32_16x16x32_bf16 v[106:109], v[158:161], v[174:177], v[106:109]
	v_mfma_f32_16x16x32_bf16 v[110:113], v[146:149], v[170:173], v[110:113]
	v_mfma_f32_16x16x32_bf16 v[110:113], v[150:153], v[174:177], v[110:113]
	v_mfma_f32_16x16x32_bf16 v[118:121], v[114:117], v[170:173], v[118:121]
	v_mfma_f32_16x16x32_bf16 v[118:121], v[134:137], v[174:177], v[118:121]
	v_mfma_f32_16x16x32_bf16 v[122:125], v[74:77], v[170:173], v[122:125]
	v_mfma_f32_16x16x32_bf16 v[122:125], v[94:97], v[174:177], v[122:125]
	v_mfma_f32_16x16x32_bf16 v[102:105], v[74:77], v[188:191], v[102:105]
	v_mfma_f32_16x16x32_bf16 v[102:105], v[94:97], v[202:205], v[102:105]
	v_mfma_f32_16x16x32_bf16 v[98:101], v[114:117], v[188:191], v[98:101]
	v_mfma_f32_16x16x32_bf16 v[98:101], v[134:137], v[202:205], v[98:101]
	v_mfma_f32_16x16x32_bf16 v[90:93], v[146:149], v[188:191], v[90:93]
	v_mfma_f32_16x16x32_bf16 v[90:93], v[150:153], v[202:205], v[90:93]
	v_mfma_f32_16x16x32_bf16 v[86:89], v[154:157], v[188:191], v[86:89]
	v_mfma_f32_16x16x32_bf16 v[86:89], v[158:161], v[202:205], v[86:89]
	v_mfma_f32_16x16x32_bf16 v[66:69], v[154:157], v[206:209], v[66:69]
	v_mfma_f32_16x16x32_bf16 v[66:69], v[158:161], v[210:213], v[66:69]
	v_mfma_f32_16x16x32_bf16 v[70:73], v[146:149], v[206:209], v[70:73]
	v_mfma_f32_16x16x32_bf16 v[70:73], v[150:153], v[210:213], v[70:73]
	v_mfma_f32_16x16x32_bf16 v[78:81], v[114:117], v[206:209], v[78:81]
	v_mfma_f32_16x16x32_bf16 v[78:81], v[134:137], v[210:213], v[78:81]
	v_mfma_f32_16x16x32_bf16 v[82:85], v[74:77], v[206:209], v[82:85]
	v_mfma_f32_16x16x32_bf16 v[82:85], v[94:97], v[210:213], v[82:85]
	s_setprio 0
	s_barrier
	ds_read_b128 v[162:165], v186 offset:49152
	ds_read_b128 v[166:169], v186 offset:50176
	ds_read_b128 v[170:173], v186 offset:51200
	ds_read_b128 v[174:177], v186 offset:52224
	ds_read_b128 v[188:191], v186 offset:53248
	ds_read_b128 v[202:205], v186 offset:54272
	ds_read_b128 v[206:209], v186 offset:55296
	ds_read_b128 v[210:213], v186 offset:56320
	s_add_u32 s30, s58, 0x80
	s_addc_u32 s31, s59, 0
	s_mov_b32 m0, s94
	s_nop 0
	global_load_lds_dwordx4 v180, s[30:31]
	s_nop 0
	s_mov_b32 m0, s95
	s_nop 0
	global_load_lds_dwordx4 v182, s[30:31]
	s_add_u32 s30, s58, 0x40080
	s_addc_u32 s31, s59, 0
	s_mov_b32 m0, s17
	s_nop 0
	global_load_lds_dwordx4 v180, s[30:31]
	s_nop 0
	s_mov_b32 m0, s53
	s_nop 0
	global_load_lds_dwordx4 v182, s[30:31]
	s_nop 0
	s_mov_b32 m0, s96
	s_nop 0
	global_load_lds_dwordx4 v0, s[56:57]
	s_nop 0
	s_mov_b32 m0, s97
	s_nop 0
	global_load_lds_dwordx4 v181, s[56:57]
	s_waitcnt vmcnt(8)
	s_waitcnt lgkmcnt(0)
	s_barrier
	s_setprio 1
	s_waitcnt lgkmcnt(0)
	v_mfma_f32_16x16x32_bf16 v[62:65], v[74:77], v[162:165], v[62:65]
	v_mfma_f32_16x16x32_bf16 v[62:65], v[94:97], v[166:169], v[62:65]
	v_mfma_f32_16x16x32_bf16 v[58:61], v[114:117], v[162:165], v[58:61]
	v_mfma_f32_16x16x32_bf16 v[58:61], v[134:137], v[166:169], v[58:61]
	v_mfma_f32_16x16x32_bf16 v[54:57], v[146:149], v[162:165], v[54:57]
	v_mfma_f32_16x16x32_bf16 v[54:57], v[150:153], v[166:169], v[54:57]
	v_mfma_f32_16x16x32_bf16 v[50:53], v[154:157], v[162:165], v[50:53]
	v_mfma_f32_16x16x32_bf16 v[50:53], v[158:161], v[166:169], v[50:53]
	v_mfma_f32_16x16x32_bf16 v[34:37], v[154:157], v[170:173], v[34:37]
	v_mfma_f32_16x16x32_bf16 v[34:37], v[158:161], v[174:177], v[34:37]
	v_mfma_f32_16x16x32_bf16 v[38:41], v[146:149], v[170:173], v[38:41]
	v_mfma_f32_16x16x32_bf16 v[38:41], v[150:153], v[174:177], v[38:41]
	v_mfma_f32_16x16x32_bf16 v[42:45], v[114:117], v[170:173], v[42:45]
	v_mfma_f32_16x16x32_bf16 v[42:45], v[134:137], v[174:177], v[42:45]
	v_mfma_f32_16x16x32_bf16 v[46:49], v[74:77], v[170:173], v[46:49]
	v_mfma_f32_16x16x32_bf16 v[46:49], v[94:97], v[174:177], v[46:49]
	v_mfma_f32_16x16x32_bf16 v[30:33], v[74:77], v[188:191], v[30:33]
	v_mfma_f32_16x16x32_bf16 v[30:33], v[94:97], v[202:205], v[30:33]
	v_mfma_f32_16x16x32_bf16 v[26:29], v[114:117], v[188:191], v[26:29]
	v_mfma_f32_16x16x32_bf16 v[26:29], v[134:137], v[202:205], v[26:29]
	v_mfma_f32_16x16x32_bf16 v[22:25], v[146:149], v[188:191], v[22:25]
	v_mfma_f32_16x16x32_bf16 v[22:25], v[150:153], v[202:205], v[22:25]
	v_mfma_f32_16x16x32_bf16 v[18:21], v[154:157], v[188:191], v[18:21]
	v_mfma_f32_16x16x32_bf16 v[18:21], v[158:161], v[202:205], v[18:21]
	v_mfma_f32_16x16x32_bf16 v[2:5], v[154:157], v[206:209], v[2:5]
	v_mfma_f32_16x16x32_bf16 v[2:5], v[158:161], v[210:213], v[2:5]
	v_mfma_f32_16x16x32_bf16 v[6:9], v[146:149], v[206:209], v[6:9]
	v_mfma_f32_16x16x32_bf16 v[6:9], v[150:153], v[210:213], v[6:9]
	v_mfma_f32_16x16x32_bf16 v[10:13], v[114:117], v[206:209], v[10:13]
	v_mfma_f32_16x16x32_bf16 v[10:13], v[134:137], v[210:213], v[10:13]
	v_mfma_f32_16x16x32_bf16 v[14:17], v[74:77], v[206:209], v[14:17]
	v_mfma_f32_16x16x32_bf16 v[14:17], v[94:97], v[210:213], v[14:17]
	s_setprio 0
	s_barrier
	s_add_i32 s50, s50, 2
	s_add_u32 s41, s41, 0x100
	s_addc_u32 s49, s49, 0
	s_add_u32 s92, s92, 0x100
	s_addc_u32 s93, s93, 0
	s_cmp_gt_u32 s50, 13
	s_cbranch_scc0 .LBB0_306
	v_readlane_b32 s4, v254, 46
	v_readlane_b32 s5, v254, 47
	s_and_b64 vcc, exec, s[4:5]
	s_cbranch_vccz .LBB0_309
	s_barrier

; #define PG8_STAGE(bufoff, gbase, voff) do { _Pragma("unroll") for (int _i = 0; _i < 2; ++_i) { \
;         const unsigned _m0 = ldsb + (unsigned)((bufoff) + _i * 8192); const char* _gb = (const char*)(gbase); \
;         asm volatile("s_mov_b32 m0, %0\n\ts_nop 0\n\tglobal_load_lds_dwordx4 %1, %2" :: "s"(_m0), "v"((voff)[_i]), "s"(_gb) : "m0", "memory"); } } while (0)
; #define PG8_LDA(dst, b, h) do { _Pragma("unroll") for (int m = 0; m < 4; ++m) _Pragma("unroll") for (int k = 0; k < 2; ++k) dst[m][k] = *(const LAS bf16x8*)(lds + PG8_SA(b, h) + aoff + m * 2048 + k * 1024); } while (0)
; #define PG8_LDB(dst, b, h) do { _Pragma("unroll") for (int n = 0; n < 2; ++n) _Pragma("unroll") for (int k = 0; k < 2; ++k) dst[n][k] = *(const LAS bf16x8*)(lds + PG8_SB(b, h) + boff + n * 2048 + k * 1024); } while (0)
; #define PG8_MMA(ai, bj, At, Bt) do { __builtin_amdgcn_s_setprio(1); _Pragma("unroll") for (int m = 0; m < 4; ++m) _Pragma("unroll") for (int n = 0; n < 2; ++n) _Pragma("unroll") for (int k = 0; k < 2; ++k) \
;         acc[ai][bj][m][n] = __builtin_amdgcn_mfma_f32_16x16x32_bf16(Bt[n][k], At[m][k], acc[ai][bj][m][n], 0, 0, 0); __builtin_amdgcn_s_setprio(0); } while (0)
; template <class Epi, bool ALIGN_EPI>
; __device__ __forceinline__ void gemm_phase(LAS unsigned char* lds, const Gemm g, const StaticOrder& S, const Epi& E) {
;     ...
;             PG8_LDB(B0, 0, 0); PG8_LDB(B1, 0, 1); PG8_SCHED; PG8_LDA(At, 0, 0); PG8_STAGE(PG8_SA(1, 1), a1 + hstepA, voffA);
;             PG8_WAIT_V(8); PG8_WAIT_L(0); PG8_BAR; PG8_MMA(0, 0, At, B0); PG8_MMA(0, 1, At, B1); PG8_BAR; PG8_SCHED;
;             PG8_LDA(At, 0, 1); PG8_STAGE(PG8_SB(0, 0), b2, voffB); PG8_STAGE(PG8_SB(0, 1), b2 + hstepB, voffB); PG8_STAGE(PG8_SA(0, 0), a2, voffA);
;             PG8_WAIT_V(8); PG8_WAIT_L(0); PG8_BAR; PG8_MMA(1, 0, At, B0); PG8_MMA(1, 1, At, B1); PG8_BAR; PG8_SCHED;
;             PG8_LDB(B0, 1, 0); PG8_LDB(B1, 1, 1); PG8_SCHED; PG8_LDA(At, 1, 0); PG8_STAGE(PG8_SA(0, 1), a2 + hstepA, voffA);
;             PG8_WAIT_V(8); PG8_WAIT_L(0); PG8_BAR; PG8_MMA(0, 0, At, B0); PG8_MMA(0, 1, At, B1); PG8_BAR; PG8_SCHED;
;             PG8_LDA(At, 1, 1); PG8_STAGE(PG8_SB(1, 0), b3, voffB); PG8_STAGE(PG8_SB(1, 1), b3 + hstepB, voffB); PG8_STAGE(PG8_SA(1, 0), a3, voffA);
;             PG8_WAIT_V(8); PG8_WAIT_L(0); PG8_BAR; PG8_MMA(1, 0, At, B0); PG8_MMA(1, 1, At, B1); PG8_BAR; PG8_SCHED;
.LBB0_349:
	v_add_u32_e32 v0, 0x10000, v187
	ds_read_b128 v[34:37], v0
	ds_read_b128 v[54:57], v0 offset:1024
	ds_read_b128 v[74:77], v0 offset:2048
	ds_read_b128 v[94:97], v0 offset:3072
	v_add_u32_e32 v0, 0x14000, v187
	ds_read_b128 v[110:113], v0
	ds_read_b128 v[126:129], v0 offset:1024
	ds_read_b128 v[146:149], v0 offset:2048
	ds_read_b128 v[160:163], v0 offset:3072
	s_add_u32 s38, s36, 0xfffc0080
	s_addc_u32 s39, s37, -1
	s_cmp_eq_u32 s50, 12
	s_cselect_b32 s54, s5, s38
	s_cselect_b32 s55, s4, s39
	s_cselect_b32 s48, s27, s29
	s_cselect_b32 s49, s11, s41
	s_add_u32 s38, s54, 0x80
	s_addc_u32 s39, s55, 0
	ds_read_b128 v[164:167], v188
	ds_read_b128 v[168:171], v188 offset:1024
	ds_read_b128 v[172:175], v188 offset:2048
	ds_read_b128 v[176:179], v188 offset:3072
	ds_read_b128 v[190:193], v188 offset:4096
	ds_read_b128 v[202:205], v188 offset:5120
	ds_read_b128 v[206:209], v188 offset:6144
	ds_read_b128 v[210:213], v188 offset:7168
	s_mov_b32 m0, s91
	s_nop 0
	global_load_lds_dwordx4 v180, s[36:37]
	s_nop 0
	s_mov_b32 m0, s93
	s_nop 0
	global_load_lds_dwordx4 v182, s[36:37]
	s_waitcnt vmcnt(8)
	s_waitcnt lgkmcnt(0)
	s_barrier
	s_setprio 1
	s_waitcnt lgkmcnt(0)
	v_mfma_f32_16x16x32_bf16 v[154:157], v[34:37], v[164:167], v[154:157]
	v_mfma_f32_16x16x32_bf16 v[154:157], v[54:57], v[168:171], v[154:157]
	v_mfma_f32_16x16x32_bf16 v[150:153], v[74:77], v[164:167], v[150:153]
	v_mfma_f32_16x16x32_bf16 v[150:153], v[94:97], v[168:171], v[150:153]
	v_mfma_f32_16x16x32_bf16 v[142:145], v[110:113], v[164:167], v[142:145]
	v_mfma_f32_16x16x32_bf16 v[142:145], v[126:129], v[168:171], v[142:145]
	v_mfma_f32_16x16x32_bf16 v[138:141], v[146:149], v[164:167], v[138:141]
	v_mfma_f32_16x16x32_bf16 v[138:141], v[160:163], v[168:171], v[138:141]
	v_mfma_f32_16x16x32_bf16 v[118:121], v[146:149], v[172:175], v[118:121]
	v_mfma_f32_16x16x32_bf16 v[118:121], v[160:163], v[176:179], v[118:121]
	v_mfma_f32_16x16x32_bf16 v[122:125], v[110:113], v[172:175], v[122:125]
	v_mfma_f32_16x16x32_bf16 v[122:125], v[126:129], v[176:179], v[122:125]
	v_mfma_f32_16x16x32_bf16 v[130:133], v[74:77], v[172:175], v[130:133]
	v_mfma_f32_16x16x32_bf16 v[130:133], v[94:97], v[176:179], v[130:133]
	v_mfma_f32_16x16x32_bf16 v[134:137], v[34:37], v[172:175], v[134:137]
	v_mfma_f32_16x16x32_bf16 v[134:137], v[54:57], v[176:179], v[134:137]
	v_mfma_f32_16x16x32_bf16 v[114:117], v[34:37], v[190:193], v[114:117]
	v_mfma_f32_16x16x32_bf16 v[114:117], v[54:57], v[202:205], v[114:117]
	v_mfma_f32_16x16x32_bf16 v[106:109], v[74:77], v[190:193], v[106:109]
	v_mfma_f32_16x16x32_bf16 v[106:109], v[94:97], v[202:205], v[106:109]
	v_mfma_f32_16x16x32_bf16 v[102:105], v[110:113], v[190:193], v[102:105]
	v_mfma_f32_16x16x32_bf16 v[102:105], v[126:129], v[202:205], v[102:105]
	v_mfma_f32_16x16x32_bf16 v[98:101], v[146:149], v[190:193], v[98:101]
	v_mfma_f32_16x16x32_bf16 v[98:101], v[160:163], v[202:205], v[98:101]
	v_mfma_f32_16x16x32_bf16 v[78:81], v[146:149], v[206:209], v[78:81]
	v_mfma_f32_16x16x32_bf16 v[78:81], v[160:163], v[210:213], v[78:81]
	v_mfma_f32_16x16x32_bf16 v[82:85], v[110:113], v[206:209], v[82:85]
	v_mfma_f32_16x16x32_bf16 v[82:85], v[126:129], v[210:213], v[82:85]
	v_mfma_f32_16x16x32_bf16 v[86:89], v[74:77], v[206:209], v[86:89]
	v_mfma_f32_16x16x32_bf16 v[86:89], v[94:97], v[210:213], v[86:89]
	v_mfma_f32_16x16x32_bf16 v[90:93], v[34:37], v[206:209], v[90:93]
	v_mfma_f32_16x16x32_bf16 v[90:93], v[54:57], v[210:213], v[90:93]
	s_setprio 0
	s_barrier
	ds_read_b128 v[164:167], v188 offset:16384
	ds_read_b128 v[168:171], v188 offset:17408
	ds_read_b128 v[172:175], v188 offset:18432
	ds_read_b128 v[176:179], v188 offset:19456
	ds_read_b128 v[190:193], v188 offset:20480
	ds_read_b128 v[202:205], v188 offset:21504
	ds_read_b128 v[206:209], v188 offset:22528
	ds_read_b128 v[210:213], v188 offset:23552
	s_mov_b32 m0, s43
	s_nop 0
	global_load_lds_dwordx4 v181, s[48:49]
	s_add_u32 s96, s48, 0x40000
	s_mov_b32 m0, s44
	s_nop 0
	global_load_lds_dwordx4 v183, s[48:49]
	s_addc_u32 s97, s49, 0
	s_mov_b32 m0, s45
	s_nop 0
	global_load_lds_dwordx4 v181, s[96:97]
	s_nop 0
	s_mov_b32 m0, s56
	s_nop 0
	global_load_lds_dwordx4 v183, s[96:97]
	s_nop 0
	s_mov_b32 m0, s42
	s_nop 0
	global_load_lds_dwordx4 v180, s[54:55]
	s_nop 0
	s_mov_b32 m0, s57
	s_nop 0
	global_load_lds_dwordx4 v182, s[54:55]
	s_waitcnt vmcnt(8)
	s_waitcnt lgkmcnt(0)
	s_barrier
	s_setprio 1
	s_waitcnt lgkmcnt(0)
	v_mfma_f32_16x16x32_bf16 v[70:73], v[34:37], v[164:167], v[70:73]
	v_mfma_f32_16x16x32_bf16 v[66:69], v[74:77], v[164:167], v[66:69]
	v_mfma_f32_16x16x32_bf16 v[50:53], v[34:37], v[172:175], v[50:53]
	v_mfma_f32_16x16x32_bf16 v[46:49], v[74:77], v[172:175], v[46:49]
	v_mfma_f32_16x16x32_bf16 v[30:33], v[34:37], v[190:193], v[30:33]
	v_mfma_f32_16x16x32_bf16 v[26:29], v[74:77], v[190:193], v[26:29]
	v_mfma_f32_16x16x32_bf16 v[14:17], v[34:37], v[206:209], v[14:17]
	v_mfma_f32_16x16x32_bf16 v[10:13], v[74:77], v[206:209], v[10:13]
	v_mfma_f32_16x16x32_bf16 v[70:73], v[54:57], v[168:171], v[70:73]
	v_mfma_f32_16x16x32_bf16 v[66:69], v[94:97], v[168:171], v[66:69]
	v_mfma_f32_16x16x32_bf16 v[50:53], v[54:57], v[176:179], v[50:53]
	v_mfma_f32_16x16x32_bf16 v[46:49], v[94:97], v[176:179], v[46:49]
	v_mfma_f32_16x16x32_bf16 v[30:33], v[54:57], v[202:205], v[30:33]
	v_mfma_f32_16x16x32_bf16 v[26:29], v[94:97], v[202:205], v[26:29]
	v_mfma_f32_16x16x32_bf16 v[14:17], v[54:57], v[210:213], v[14:17]
	v_mfma_f32_16x16x32_bf16 v[10:13], v[94:97], v[210:213], v[10:13]
	s_setprio 0
	s_setprio 1
	v_mfma_f32_16x16x32_bf16 v[42:45], v[110:113], v[172:175], v[42:45]
	v_mfma_f32_16x16x32_bf16 v[38:41], v[146:149], v[172:175], v[38:41]
	v_mfma_f32_16x16x32_bf16 v[22:25], v[110:113], v[190:193], v[22:25]
	v_mfma_f32_16x16x32_bf16 v[18:21], v[146:149], v[190:193], v[18:21]
	v_mfma_f32_16x16x32_bf16 v[6:9], v[110:113], v[206:209], v[6:9]
	v_mfma_f32_16x16x32_bf16 v[2:5], v[146:149], v[206:209], v[2:5]
	v_mfma_f32_16x16x32_bf16 v[34:37], v[110:113], v[164:167], v[62:65]
	v_mfma_f32_16x16x32_bf16 v[54:57], v[146:149], v[164:167], v[58:61]
	v_mfma_f32_16x16x32_bf16 v[42:45], v[126:129], v[176:179], v[42:45]
	v_mfma_f32_16x16x32_bf16 v[38:41], v[160:163], v[176:179], v[38:41]
	v_mfma_f32_16x16x32_bf16 v[22:25], v[126:129], v[202:205], v[22:25]
	v_mfma_f32_16x16x32_bf16 v[18:21], v[160:163], v[202:205], v[18:21]
	v_mfma_f32_16x16x32_bf16 v[6:9], v[126:129], v[210:213], v[6:9]
	v_mfma_f32_16x16x32_bf16 v[2:5], v[160:163], v[210:213], v[2:5]
	v_mfma_f32_16x16x32_bf16 v[34:37], v[126:129], v[168:171], v[34:37]
	v_mfma_f32_16x16x32_bf16 v[54:57], v[160:163], v[168:171], v[54:57]
	s_setprio 0
	s_barrier
; #define PG8_STAGE(bufoff, gbase, voff) do { _Pragma("unroll") for (int _i = 0; _i < 2; ++_i) { \
;         const unsigned _m0 = ldsb + (unsigned)((bufoff) + _i * 8192); const char* _gb = (const char*)(gbase); \
;         asm volatile("s_mov_b32 m0, %0\n\ts_nop 0\n\tglobal_load_lds_dwordx4 %1, %2" :: "s"(_m0), "v"((voff)[_i]), "s"(_gb) : "m0", "memory"); } } while (0)
; #define PG8_LDA(dst, b, h) do { _Pragma("unroll") for (int m = 0; m < 4; ++m) _Pragma("unroll") for (int k = 0; k < 2; ++k) dst[m][k] = *(const LAS bf16x8*)(lds + PG8_SA(b, h) + aoff + m * 2048 + k * 1024); } while (0)
; #define PG8_LDB(dst, b, h) do { _Pragma("unroll") for (int n = 0; n < 2; ++n) _Pragma("unroll") for (int k = 0; k < 2; ++k) dst[n][k] = *(const LAS bf16x8*)(lds + PG8_SB(b, h) + boff + n * 2048 + k * 1024); } while (0)
; #define PG8_MMA(ai, bj, At, Bt) do { __builtin_amdgcn_s_setprio(1); _Pragma("unroll") for (int m = 0; m < 4; ++m) _Pragma("unroll") for (int n = 0; n < 2; ++n) _Pragma("unroll") for (int k = 0; k < 2; ++k) \
;         acc[ai][bj][m][n] = __builtin_amdgcn_mfma_f32_16x16x32_bf16(Bt[n][k], At[m][k], acc[ai][bj][m][n], 0, 0, 0); __builtin_amdgcn_s_setprio(0); } while (0)
; template <class Epi, bool ALIGN_EPI>
; __device__ __forceinline__ void gemm_phase(LAS unsigned char* lds, const Gemm g, const StaticOrder& S, const Epi& E) {
;     ...
;             PG8_LDB(B0, 0, 0); PG8_LDB(B1, 0, 1); PG8_SCHED; PG8_LDA(At, 0, 0); PG8_STAGE(PG8_SA(1, 1), a1 + hstepA, voffA);
;             PG8_WAIT_V(8); PG8_WAIT_L(0); PG8_BAR; PG8_MMA(0, 0, At, B0); PG8_MMA(0, 1, At, B1); PG8_BAR; PG8_SCHED;
;             PG8_LDA(At, 0, 1); PG8_STAGE(PG8_SB(0, 0), b2, voffB); PG8_STAGE(PG8_SB(0, 1), b2 + hstepB, voffB); PG8_STAGE(PG8_SA(0, 0), a2, voffA);
;             PG8_WAIT_V(8); PG8_WAIT_L(0); PG8_BAR; PG8_MMA(1, 0, At, B0); PG8_MMA(1, 1, At, B1); PG8_BAR; PG8_SCHED;
;             PG8_LDB(B0, 1, 0); PG8_LDB(B1, 1, 1); PG8_SCHED; PG8_LDA(At, 1, 0); PG8_STAGE(PG8_SA(0, 1), a2 + hstepA, voffA);
;             PG8_WAIT_V(8); PG8_WAIT_L(0); PG8_BAR; PG8_MMA(0, 0, At, B0); PG8_MMA(0, 1, At, B1); PG8_BAR; PG8_SCHED;
;             PG8_LDA(At, 1, 1); PG8_STAGE(PG8_SB(1, 0), b3, voffB); PG8_STAGE(PG8_SB(1, 1), b3 + hstepB, voffB); PG8_STAGE(PG8_SA(1, 0), a3, voffA);
;             PG8_WAIT_V(8); PG8_WAIT_L(0); PG8_BAR; PG8_MMA(1, 0, At, B0); PG8_MMA(1, 1, At, B1); PG8_BAR; PG8_SCHED;
	v_add_u32_e32 v0, 0x18000, v187
	ds_read_b128 v[58:61], v0
	ds_read_b128 v[62:65], v0 offset:1024
	ds_read_b128 v[74:77], v0 offset:2048
	ds_read_b128 v[94:97], v0 offset:3072
	v_add_u32_e32 v0, 0x1c000, v187
	ds_read_b128 v[110:113], v0
	ds_read_b128 v[126:129], v0 offset:1024
	ds_read_b128 v[146:149], v0 offset:2048
	ds_read_b128 v[160:163], v0 offset:3072
	ds_read_b128 v[164:167], v188 offset:32768
	ds_read_b128 v[168:171], v188 offset:33792
	ds_read_b128 v[172:175], v188 offset:34816
	ds_read_b128 v[176:179], v188 offset:35840
	ds_read_b128 v[190:193], v188 offset:36864
	ds_read_b128 v[202:205], v188 offset:37888
	ds_read_b128 v[206:209], v188 offset:38912
	ds_read_b128 v[210:213], v188 offset:39936
	s_add_u32 s54, s54, 0x40000
	s_addc_u32 s55, s55, 0
	s_mov_b32 m0, s58
	s_nop 0
	global_load_lds_dwordx4 v180, s[54:55]
	s_nop 0
	s_mov_b32 m0, s59
	s_nop 0
	global_load_lds_dwordx4 v182, s[54:55]
	s_waitcnt vmcnt(8)
	s_waitcnt lgkmcnt(0)
	s_barrier
	s_setprio 1
	s_waitcnt lgkmcnt(0)
	v_mfma_f32_16x16x32_bf16 v[154:157], v[58:61], v[164:167], v[154:157]
	v_mfma_f32_16x16x32_bf16 v[154:157], v[62:65], v[168:171], v[154:157]
	v_mfma_f32_16x16x32_bf16 v[150:153], v[74:77], v[164:167], v[150:153]
	v_mfma_f32_16x16x32_bf16 v[150:153], v[94:97], v[168:171], v[150:153]
	v_mfma_f32_16x16x32_bf16 v[142:145], v[110:113], v[164:167], v[142:145]
	v_mfma_f32_16x16x32_bf16 v[142:145], v[126:129], v[168:171], v[142:145]
	v_mfma_f32_16x16x32_bf16 v[138:141], v[146:149], v[164:167], v[138:141]
	v_mfma_f32_16x16x32_bf16 v[138:141], v[160:163], v[168:171], v[138:141]
	v_mfma_f32_16x16x32_bf16 v[118:121], v[146:149], v[172:175], v[118:121]
	v_mfma_f32_16x16x32_bf16 v[118:121], v[160:163], v[176:179], v[118:121]
	v_mfma_f32_16x16x32_bf16 v[122:125], v[110:113], v[172:175], v[122:125]
	v_mfma_f32_16x16x32_bf16 v[122:125], v[126:129], v[176:179], v[122:125]
	v_mfma_f32_16x16x32_bf16 v[130:133], v[74:77], v[172:175], v[130:133]
	v_mfma_f32_16x16x32_bf16 v[130:133], v[94:97], v[176:179], v[130:133]
	v_mfma_f32_16x16x32_bf16 v[134:137], v[58:61], v[172:175], v[134:137]
	v_mfma_f32_16x16x32_bf16 v[134:137], v[62:65], v[176:179], v[134:137]
	v_mfma_f32_16x16x32_bf16 v[114:117], v[58:61], v[190:193], v[114:117]
	v_mfma_f32_16x16x32_bf16 v[114:117], v[62:65], v[202:205], v[114:117]
	v_mfma_f32_16x16x32_bf16 v[106:109], v[74:77], v[190:193], v[106:109]
	v_mfma_f32_16x16x32_bf16 v[106:109], v[94:97], v[202:205], v[106:109]
	v_mfma_f32_16x16x32_bf16 v[102:105], v[110:113], v[190:193], v[102:105]
	v_mfma_f32_16x16x32_bf16 v[102:105], v[126:129], v[202:205], v[102:105]
	v_mfma_f32_16x16x32_bf16 v[98:101], v[146:149], v[190:193], v[98:101]
	v_mfma_f32_16x16x32_bf16 v[98:101], v[160:163], v[202:205], v[98:101]
	v_mfma_f32_16x16x32_bf16 v[78:81], v[146:149], v[206:209], v[78:81]
	v_mfma_f32_16x16x32_bf16 v[78:81], v[160:163], v[210:213], v[78:81]
	v_mfma_f32_16x16x32_bf16 v[82:85], v[110:113], v[206:209], v[82:85]
	v_mfma_f32_16x16x32_bf16 v[82:85], v[126:129], v[210:213], v[82:85]
	v_mfma_f32_16x16x32_bf16 v[86:89], v[74:77], v[206:209], v[86:89]
	v_mfma_f32_16x16x32_bf16 v[86:89], v[94:97], v[210:213], v[86:89]
	v_mfma_f32_16x16x32_bf16 v[90:93], v[58:61], v[206:209], v[90:93]
	v_mfma_f32_16x16x32_bf16 v[90:93], v[62:65], v[210:213], v[90:93]
	s_setprio 0
	s_barrier
	ds_read_b128 v[164:167], v188 offset:49152
	ds_read_b128 v[168:171], v188 offset:50176
	ds_read_b128 v[172:175], v188 offset:51200
	ds_read_b128 v[176:179], v188 offset:52224
	ds_read_b128 v[190:193], v188 offset:53248
	ds_read_b128 v[202:205], v188 offset:54272
	ds_read_b128 v[206:209], v188 offset:55296
	ds_read_b128 v[210:213], v188 offset:56320
	s_add_u32 s54, s48, 0x80
	s_addc_u32 s55, s49, 0
	s_mov_b32 m0, s17
	s_nop 0
	global_load_lds_dwordx4 v181, s[54:55]
	s_add_u32 s48, s48, 0x40080
	s_mov_b32 m0, s60
	s_nop 0
	global_load_lds_dwordx4 v183, s[54:55]
	s_addc_u32 s49, s49, 0
	s_mov_b32 m0, s89
	s_nop 0
	global_load_lds_dwordx4 v181, s[48:49]
	s_nop 0
	s_mov_b32 m0, s90
	s_nop 0
	global_load_lds_dwordx4 v183, s[48:49]
	s_nop 0
	s_mov_b32 m0, s61
	s_nop 0
	global_load_lds_dwordx4 v180, s[38:39]
	s_nop 0
	s_mov_b32 m0, s88
	s_nop 0
	global_load_lds_dwordx4 v182, s[38:39]
	s_waitcnt vmcnt(8)
	s_waitcnt lgkmcnt(0)
	s_barrier
	s_setprio 1
	s_waitcnt lgkmcnt(0)
	v_mfma_f32_16x16x32_bf16 v[70:73], v[58:61], v[164:167], v[70:73]
	v_mfma_f32_16x16x32_bf16 v[66:69], v[74:77], v[164:167], v[66:69]
	v_mfma_f32_16x16x32_bf16 v[50:53], v[58:61], v[172:175], v[50:53]
	v_mfma_f32_16x16x32_bf16 v[46:49], v[74:77], v[172:175], v[46:49]
	v_mfma_f32_16x16x32_bf16 v[30:33], v[58:61], v[190:193], v[30:33]
	v_mfma_f32_16x16x32_bf16 v[26:29], v[74:77], v[190:193], v[26:29]
	v_mfma_f32_16x16x32_bf16 v[14:17], v[58:61], v[206:209], v[14:17]
	v_mfma_f32_16x16x32_bf16 v[10:13], v[74:77], v[206:209], v[10:13]
	v_mfma_f32_16x16x32_bf16 v[70:73], v[62:65], v[168:171], v[70:73]
	v_mfma_f32_16x16x32_bf16 v[66:69], v[94:97], v[168:171], v[66:69]
	v_mfma_f32_16x16x32_bf16 v[50:53], v[62:65], v[176:179], v[50:53]
	v_mfma_f32_16x16x32_bf16 v[46:49], v[94:97], v[176:179], v[46:49]
	v_mfma_f32_16x16x32_bf16 v[30:33], v[62:65], v[202:205], v[30:33]
	v_mfma_f32_16x16x32_bf16 v[26:29], v[94:97], v[202:205], v[26:29]
	v_mfma_f32_16x16x32_bf16 v[14:17], v[62:65], v[210:213], v[14:17]
	v_mfma_f32_16x16x32_bf16 v[10:13], v[94:97], v[210:213], v[10:13]
	s_setprio 0
	s_setprio 1
	v_mfma_f32_16x16x32_bf16 v[34:37], v[110:113], v[164:167], v[34:37]
	v_mfma_f32_16x16x32_bf16 v[62:65], v[126:129], v[168:171], v[34:37]
	v_mfma_f32_16x16x32_bf16 v[34:37], v[146:149], v[164:167], v[54:57]
	v_mfma_f32_16x16x32_bf16 v[58:61], v[160:163], v[168:171], v[34:37]
	v_mfma_f32_16x16x32_bf16 v[34:37], v[110:113], v[172:175], v[42:45]
	v_mfma_f32_16x16x32_bf16 v[42:45], v[126:129], v[176:179], v[34:37]
	v_mfma_f32_16x16x32_bf16 v[34:37], v[146:149], v[172:175], v[38:41]
	v_mfma_f32_16x16x32_bf16 v[22:25], v[110:113], v[190:193], v[22:25]
	v_mfma_f32_16x16x32_bf16 v[18:21], v[146:149], v[190:193], v[18:21]
	v_mfma_f32_16x16x32_bf16 v[6:9], v[110:113], v[206:209], v[6:9]
	v_mfma_f32_16x16x32_bf16 v[2:5], v[146:149], v[206:209], v[2:5]
	v_mfma_f32_16x16x32_bf16 v[38:41], v[160:163], v[176:179], v[34:37]
	v_mfma_f32_16x16x32_bf16 v[22:25], v[126:129], v[202:205], v[22:25]
	v_mfma_f32_16x16x32_bf16 v[18:21], v[160:163], v[202:205], v[18:21]
	v_mfma_f32_16x16x32_bf16 v[6:9], v[126:129], v[210:213], v[6:9]
	v_mfma_f32_16x16x32_bf16 v[2:5], v[160:163], v[210:213], v[2:5]
	s_setprio 0
	s_barrier
	s_add_i32 s50, s50, 2
	s_add_u32 s29, s29, 0x100
	s_addc_u32 s41, s41, 0
	s_add_u32 s36, s36, 0x100
	s_addc_u32 s37, s37, 0
	s_cmp_gt_u32 s50, 13
	s_cbranch_scc0 .LBB0_349
	s_and_b64 vcc, exec, s[24:25]
	s_cbranch_vccz .LBB0_352
	s_barrier
